# speedup vs baseline: 1.0590x; 1.0087x over previous
; DEV unsigned pack2(float a, float b) { return (unsigned)f2bf(a) | ((unsigned)f2bf(b) << 16); }
; DEV float lo2f(unsigned v) { return __uint_as_float(v << 16); }
; DEV float hi2f(unsigned v) { return __uint_as_float(v & 0xffff0000u); }
; PHASE void lru_phase(const Params& p, int layer, const u16* __restrict__ GC, u16* __restrict__ OC, float* __restrict__ LA, ...
;     ...
; #pragma unroll
;       for (int i = 0; i < 16; ++i) {
;         int tt = t0 + tg * 16 + i;
;         unsigned cur = *(const unsigned*)(GC + (base + tt) * 4096 + ch);
;         float y0 = b0 + w0[0] * lo2f(win[0]) + w0[1] * lo2f(win[1]) + w0[2] * lo2f(win[2]) + w0[3] * lo2f(cur);
;         float y1 = b1 + w1[0] * hi2f(win[0]) + w1[1] * hi2f(win[1]) + w1[2] * hi2f(win[2]) + w1[3] * hi2f(cur);
;         *(unsigned*)(sX + (tg * 16 + i) * 136 + 2 * cp) = pack2(y0, y1);
;         win[0] = win[1]; win[1] = win[2]; win[2] = cur;
;       }
.LBB0_367:
	s_or_b64 exec, exec, s[0:1]
	v_add_u32_e32 v12, s31, v66
	v_ashrrev_i32_e32 v13, 31, v12
	v_lshl_add_u64 v[18:19], s[20:21], 0, v[12:13]
	v_lshlrev_b64 v[18:19], 13, v[18:19]
	v_lshl_add_u64 v[18:19], v[10:11], 0, v[18:19]
	global_load_dword v13, v[18:19], off
	v_mov_b32_e32 v208, 0x2000
	v_mov_b32_e32 v209, 0
	v_mov_b64_e32 v[210:211], v[18:19]
	v_lshl_add_u64 v[210:211], v[210:211], 0, v[208:209]
	global_load_dword v213, v[210:211], off
	v_lshl_add_u64 v[210:211], v[210:211], 0, v[208:209]
	global_load_dword v214, v[210:211], off
	v_lshl_add_u64 v[210:211], v[210:211], 0, v[208:209]
	global_load_dword v215, v[210:211], off
	v_lshl_add_u64 v[210:211], v[210:211], 0, v[208:209]
	global_load_dword v216, v[210:211], off
	v_lshl_add_u64 v[210:211], v[210:211], 0, v[208:209]
	global_load_dword v217, v[210:211], off
	v_lshl_add_u64 v[210:211], v[210:211], 0, v[208:209]
	global_load_dword v218, v[210:211], off
	v_lshl_add_u64 v[210:211], v[210:211], 0, v[208:209]
	global_load_dword v219, v[210:211], off
	v_lshl_add_u64 v[210:211], v[210:211], 0, v[208:209]
	global_load_dword v220, v[210:211], off
	v_lshl_add_u64 v[210:211], v[210:211], 0, v[208:209]
	global_load_dword v221, v[210:211], off
	v_lshl_add_u64 v[210:211], v[210:211], 0, v[208:209]
	global_load_dword v222, v[210:211], off
	v_lshl_add_u64 v[210:211], v[210:211], 0, v[208:209]
	global_load_dword v223, v[210:211], off
	v_lshl_add_u64 v[210:211], v[210:211], 0, v[208:209]
	global_load_dword v224, v[210:211], off
	v_lshl_add_u64 v[210:211], v[210:211], 0, v[208:209]
	global_load_dword v225, v[210:211], off
	v_lshl_add_u64 v[210:211], v[210:211], 0, v[208:209]
	global_load_dword v226, v[210:211], off
	v_lshl_add_u64 v[210:211], v[210:211], 0, v[208:209]
	global_load_dword v227, v[210:211], off
	s_waitcnt vmcnt(16)
	v_lshlrev_b32_e32 v17, 16, v15
	v_fma_f32 v17, v8, v17, v0
	v_lshlrev_b32_e32 v18, 16, v14
	v_and_b32_e32 v15, 0xffff0000, v15
	v_fmac_f32_e32 v17, v6, v18
	v_lshlrev_b32_e32 v19, 16, v16
	v_fma_f32 v15, v9, v15, v1
	v_and_b32_e32 v21, 0xffff0000, v14
	v_fmac_f32_e32 v17, v2, v19
	v_fmac_f32_e32 v15, v7, v21
	v_and_b32_e32 v16, 0xffff0000, v16
	v_fmac_f32_e32 v15, v3, v16
	v_readlane_b32 s0, v249, 62
	v_readlane_b32 s1, v249, 63
	s_mov_b32 s25, s1
	s_lshl_b32 s24, s26, 15
	v_lshl_add_u64 v[28:29], v[70:71], 0, s[24:25]
	v_mov_b32_e32 v105, v157
	v_mov_b32_e32 v107, v157
	v_lshl_add_u64 v[34:35], v[28:29], 0, v[104:105]
	v_lshl_add_u64 v[108:109], v[28:29], 0, v[106:107]
	s_mov_b32 s26, 0x42ce8ed0
	s_mov_b32 s27, 0xc2b17218
	s_mov_b32 s35, 0x3f2aaaab
	s_mov_b32 s36, 0x3f317218
	v_writelane_b32 v249, s0, 62
	s_mov_b32 s37, 0x33800000
	s_waitcnt vmcnt(0)
	v_lshlrev_b32_e32 v20, 16, v13
	v_fmac_f32_e32 v17, v4, v20
	v_and_b32_e32 v13, 0xffff0000, v13
	v_fmac_f32_e32 v15, v5, v13
	v_bfe_u32 v14, v17, 16, 1
	v_add3_u32 v14, v17, v14, s71
	v_bfe_u32 v17, v15, 16, 1
	v_lshrrev_b32_e32 v14, 16, v14
	v_add3_u32 v15, v15, v17, s71
	v_and_or_b32 v14, v15, s81, v14
	ds_write_b32 v133, v14
	v_or_b32_e32 v14, 1, v12
	v_ashrrev_i32_e32 v15, 31, v14
	v_lshl_add_u64 v[14:15], s[20:21], 0, v[14:15]
	v_lshlrev_b64 v[14:15], 13, v[14:15]
	v_lshl_add_u64 v[14:15], v[10:11], 0, v[14:15]
	v_mov_b32_e32 v14, v213
	v_fma_f32 v15, v8, v18, v0
	v_fmac_f32_e32 v15, v6, v19
	v_fma_f32 v18, v9, v21, v1
	v_fmac_f32_e32 v15, v2, v20
	v_fmac_f32_e32 v18, v7, v16
	v_fmac_f32_e32 v18, v3, v13
	v_fma_f32 v16, v9, v16, v1
	v_fmac_f32_e32 v16, v7, v13
	v_fma_f32 v13, v9, v13, v1
	v_writelane_b32 v249, s1, 63
	s_waitcnt vmcnt(0)
	v_lshlrev_b32_e32 v17, 16, v14
	v_fmac_f32_e32 v15, v4, v17
	v_and_b32_e32 v21, 0xffff0000, v14
	v_fmac_f32_e32 v18, v5, v21
	v_bfe_u32 v14, v15, 16, 1
	v_add3_u32 v14, v15, v14, s71
	v_bfe_u32 v15, v18, 16, 1
	v_lshrrev_b32_e32 v14, 16, v14
	v_add3_u32 v15, v18, v15, s71
	v_and_or_b32 v18, v15, s81, v14
	v_or_b32_e32 v14, 2, v12
	v_ashrrev_i32_e32 v15, 31, v14
	v_lshl_add_u64 v[14:15], s[20:21], 0, v[14:15]
	v_lshlrev_b64 v[14:15], 13, v[14:15]
	v_lshl_add_u64 v[14:15], v[10:11], 0, v[14:15]
	v_mov_b32_e32 v14, v214
	v_fma_f32 v15, v8, v19, v0
	v_fmac_f32_e32 v15, v6, v20
	v_fmac_f32_e32 v15, v2, v17
	v_fmac_f32_e32 v16, v3, v21
	v_fmac_f32_e32 v13, v7, v21
	s_waitcnt vmcnt(0)
	v_lshlrev_b32_e32 v19, 16, v14
	v_fmac_f32_e32 v15, v4, v19
	v_and_b32_e32 v22, 0xffff0000, v14
	v_fmac_f32_e32 v16, v5, v22
	v_bfe_u32 v14, v15, 16, 1
	v_add3_u32 v14, v15, v14, s71
	v_bfe_u32 v15, v16, 16, 1
	v_lshrrev_b32_e32 v14, 16, v14
	v_add3_u32 v15, v16, v15, s71
	v_and_or_b32 v14, v15, s81, v14
	ds_write2_b32 v134, v18, v14 offset1:68
	v_or_b32_e32 v14, 3, v12
	v_ashrrev_i32_e32 v15, 31, v14
	v_lshl_add_u64 v[14:15], s[20:21], 0, v[14:15]
	v_lshlrev_b64 v[14:15], 13, v[14:15]
	v_lshl_add_u64 v[14:15], v[10:11], 0, v[14:15]
	v_mov_b32_e32 v14, v215
	v_fma_f32 v15, v8, v20, v0
	v_fmac_f32_e32 v15, v6, v17
	v_fmac_f32_e32 v15, v2, v19
	v_fmac_f32_e32 v13, v3, v22
	v_fma_f32 v16, v9, v21, v1
	v_fmac_f32_e32 v16, v7, v22
	v_fma_f32 v18, v9, v22, v1
	s_waitcnt vmcnt(0)
	v_lshlrev_b32_e32 v20, 16, v14
	v_fmac_f32_e32 v15, v4, v20
	v_and_b32_e32 v23, 0xffff0000, v14
	v_fmac_f32_e32 v13, v5, v23
	v_bfe_u32 v14, v15, 16, 1
	v_add3_u32 v14, v15, v14, s71
	v_bfe_u32 v15, v13, 16, 1
	v_lshrrev_b32_e32 v14, 16, v14
	v_add3_u32 v13, v13, v15, s71
	v_and_or_b32 v13, v13, s81, v14
	v_or_b32_e32 v14, 4, v12
	v_ashrrev_i32_e32 v15, 31, v14
	v_lshl_add_u64 v[14:15], s[20:21], 0, v[14:15]
	v_lshlrev_b64 v[14:15], 13, v[14:15]
	v_lshl_add_u64 v[14:15], v[10:11], 0, v[14:15]
	v_mov_b32_e32 v14, v216
	v_fma_f32 v15, v8, v17, v0
	v_fmac_f32_e32 v15, v6, v19
	v_fmac_f32_e32 v15, v2, v20
	v_fmac_f32_e32 v16, v3, v23
	v_fmac_f32_e32 v18, v7, v23
	s_waitcnt vmcnt(0)
; DEV unsigned pack2(float a, float b) { return (unsigned)f2bf(a) | ((unsigned)f2bf(b) << 16); }
; DEV float lo2f(unsigned v) { return __uint_as_float(v << 16); }
; DEV float hi2f(unsigned v) { return __uint_as_float(v & 0xffff0000u); }
; PHASE void lru_phase(const Params& p, int layer, const u16* __restrict__ GC, u16* __restrict__ OC, float* __restrict__ LA, ...
;     ...
; #pragma unroll
;       for (int i = 0; i < 16; ++i) {
;         int tt = t0 + tg * 16 + i;
;         unsigned cur = *(const unsigned*)(GC + (base + tt) * 4096 + ch);
;         float y0 = b0 + w0[0] * lo2f(win[0]) + w0[1] * lo2f(win[1]) + w0[2] * lo2f(win[2]) + w0[3] * lo2f(cur);
;         float y1 = b1 + w1[0] * hi2f(win[0]) + w1[1] * hi2f(win[1]) + w1[2] * hi2f(win[2]) + w1[3] * hi2f(cur);
;         *(unsigned*)(sX + (tg * 16 + i) * 136 + 2 * cp) = pack2(y0, y1);
;         win[0] = win[1]; win[1] = win[2]; win[2] = cur;
;       }
	v_lshlrev_b32_e32 v17, 16, v14
	v_fmac_f32_e32 v15, v4, v17
	v_and_b32_e32 v24, 0xffff0000, v14
	v_fmac_f32_e32 v16, v5, v24
	v_bfe_u32 v14, v15, 16, 1
	v_add3_u32 v14, v15, v14, s71
	v_bfe_u32 v15, v16, 16, 1
	v_lshrrev_b32_e32 v14, 16, v14
	v_add3_u32 v15, v16, v15, s71
	v_and_or_b32 v14, v15, s81, v14
	ds_write2_b32 v134, v13, v14 offset0:136 offset1:204
	v_or_b32_e32 v14, 5, v12
	v_ashrrev_i32_e32 v15, 31, v14
	v_lshl_add_u64 v[14:15], s[20:21], 0, v[14:15]
	v_lshlrev_b64 v[14:15], 13, v[14:15]
	v_lshl_add_u64 v[14:15], v[10:11], 0, v[14:15]
	v_mov_b32_e32 v13, v217
	v_fma_f32 v14, v8, v19, v0
	v_fmac_f32_e32 v14, v6, v20
	v_fmac_f32_e32 v14, v2, v17
	v_fmac_f32_e32 v18, v3, v24
	s_waitcnt vmcnt(0)
	v_lshlrev_b32_e32 v15, 16, v13
	v_fmac_f32_e32 v14, v4, v15
	v_and_b32_e32 v16, 0xffff0000, v13
	v_fmac_f32_e32 v18, v5, v16
	v_bfe_u32 v13, v14, 16, 1
	v_add3_u32 v13, v14, v13, s71
	v_bfe_u32 v14, v18, 16, 1
	v_add3_u32 v14, v18, v14, s71
	v_or_b32_e32 v18, 6, v12
	v_ashrrev_i32_e32 v19, 31, v18
	v_lshl_add_u64 v[18:19], s[20:21], 0, v[18:19]
	v_lshlrev_b64 v[18:19], 13, v[18:19]
	v_lshrrev_b32_e32 v13, 16, v13
	v_lshl_add_u64 v[18:19], v[10:11], 0, v[18:19]
	v_and_or_b32 v21, v14, s81, v13
	v_mov_b32_e32 v14, v218
	v_fma_f32 v18, v8, v20, v0
	v_fmac_f32_e32 v18, v6, v17
	v_fma_f32 v19, v9, v23, v1
	v_fmac_f32_e32 v18, v2, v15
	v_fmac_f32_e32 v19, v7, v24
	v_fmac_f32_e32 v19, v3, v16
	s_waitcnt vmcnt(0)
	v_lshlrev_b32_e32 v13, 16, v14
	v_fmac_f32_e32 v18, v4, v13
	v_and_b32_e32 v14, 0xffff0000, v14
	v_fmac_f32_e32 v19, v5, v14
	v_bfe_u32 v20, v18, 16, 1
	v_add3_u32 v18, v18, v20, s71
	v_bfe_u32 v20, v19, 16, 1
	v_lshrrev_b32_e32 v18, 16, v18
	v_add3_u32 v19, v19, v20, s71
	v_and_or_b32 v18, v19, s81, v18
	v_add_u32_e32 v19, 0x400, v134
	v_or_b32_e32 v20, 7, v12
	ds_write2_b32 v19, v21, v18 offset0:16 offset1:84
	v_ashrrev_i32_e32 v21, 31, v20
	v_lshl_add_u64 v[20:21], s[20:21], 0, v[20:21]
	v_lshlrev_b64 v[20:21], 13, v[20:21]
	v_lshl_add_u64 v[20:21], v[10:11], 0, v[20:21]
	v_mov_b32_e32 v18, v219
	v_fma_f32 v20, v8, v17, v0
	v_fmac_f32_e32 v20, v6, v15
	v_fma_f32 v21, v9, v24, v1
	v_fmac_f32_e32 v20, v2, v13
	v_fmac_f32_e32 v21, v7, v16
	v_fmac_f32_e32 v21, v3, v14
	v_fma_f32 v15, v8, v15, v0
	v_fmac_f32_e32 v15, v6, v13
	v_fma_f32 v16, v9, v16, v1
	v_fmac_f32_e32 v16, v7, v14
	v_fma_f32 v13, v8, v13, v0
	v_fma_f32 v14, v9, v14, v1
	s_waitcnt vmcnt(0)
	v_lshlrev_b32_e32 v17, 16, v18
	v_fmac_f32_e32 v20, v4, v17
	v_and_b32_e32 v18, 0xffff0000, v18
	v_fmac_f32_e32 v21, v5, v18
	v_bfe_u32 v22, v20, 16, 1
	v_add3_u32 v20, v20, v22, s71
	v_bfe_u32 v22, v21, 16, 1
	v_lshrrev_b32_e32 v20, 16, v20
	v_add3_u32 v21, v21, v22, s71
	v_and_or_b32 v22, v21, s81, v20
	v_or_b32_e32 v20, 8, v12
	v_ashrrev_i32_e32 v21, 31, v20
	v_lshl_add_u64 v[20:21], s[20:21], 0, v[20:21]
	v_lshlrev_b64 v[20:21], 13, v[20:21]
	v_lshl_add_u64 v[20:21], v[10:11], 0, v[20:21]
	v_mov_b32_e32 v20, v220
	v_fmac_f32_e32 v15, v2, v17
	v_fmac_f32_e32 v16, v3, v18
	v_fmac_f32_e32 v13, v6, v17
	v_fmac_f32_e32 v14, v7, v18
	s_waitcnt vmcnt(0)
	v_lshlrev_b32_e32 v23, 16, v20
	v_fmac_f32_e32 v15, v4, v23
	v_and_b32_e32 v24, 0xffff0000, v20
	v_fmac_f32_e32 v16, v5, v24
	v_bfe_u32 v20, v15, 16, 1
	v_add3_u32 v15, v15, v20, s71
	v_bfe_u32 v20, v16, 16, 1
	v_add3_u32 v16, v16, v20, s71
	v_or_b32_e32 v20, 9, v12
	v_ashrrev_i32_e32 v21, 31, v20
	v_lshl_add_u64 v[20:21], s[20:21], 0, v[20:21]
	v_lshrrev_b32_e32 v15, 16, v15
	v_lshlrev_b64 v[20:21], 13, v[20:21]
	v_and_or_b32 v15, v16, s81, v15
	v_lshl_add_u64 v[20:21], v[10:11], 0, v[20:21]
	ds_write2_b32 v19, v22, v15 offset0:152 offset1:220
	v_mov_b32_e32 v15, v221
	v_fmac_f32_e32 v13, v2, v23
	v_fmac_f32_e32 v14, v3, v24
	s_waitcnt vmcnt(0)
	v_lshlrev_b32_e32 v16, 16, v15
	v_fmac_f32_e32 v13, v4, v16
	v_and_b32_e32 v19, 0xffff0000, v15
	v_fmac_f32_e32 v14, v5, v19
	v_bfe_u32 v15, v13, 16, 1
	v_add3_u32 v13, v13, v15, s71
	v_bfe_u32 v15, v14, 16, 1
	v_lshrrev_b32_e32 v13, 16, v13
	v_add3_u32 v14, v14, v15, s71
	v_and_or_b32 v13, v14, s81, v13
	v_or_b32_e32 v14, 10, v12
	v_ashrrev_i32_e32 v15, 31, v14
	v_lshl_add_u64 v[14:15], s[20:21], 0, v[14:15]
	v_lshlrev_b64 v[14:15], 13, v[14:15]
	v_lshl_add_u64 v[14:15], v[10:11], 0, v[14:15]
	v_mov_b32_e32 v14, v222
	v_fma_f32 v15, v8, v17, v0
	v_fmac_f32_e32 v15, v6, v23
	v_fma_f32 v17, v9, v18, v1
	v_fmac_f32_e32 v15, v2, v16
	v_fmac_f32_e32 v17, v7, v24
	v_fmac_f32_e32 v17, v3, v19
	s_waitcnt vmcnt(0)
	v_lshlrev_b32_e32 v20, 16, v14
	v_fmac_f32_e32 v15, v4, v20
	v_and_b32_e32 v18, 0xffff0000, v14
	v_fmac_f32_e32 v17, v5, v18
	v_bfe_u32 v14, v15, 16, 1
	v_add3_u32 v14, v15, v14, s71
	v_bfe_u32 v15, v17, 16, 1
	v_lshrrev_b32_e32 v14, 16, v14
	v_add3_u32 v15, v17, v15, s71
	v_and_or_b32 v14, v15, s81, v14
	v_add_u32_e32 v17, 0x800, v134
	ds_write2_b32 v17, v13, v14 offset0:32 offset1:100
	v_or_b32_e32 v14, 11, v12
	v_ashrrev_i32_e32 v15, 31, v14
	v_lshl_add_u64 v[14:15], s[20:21], 0, v[14:15]
	v_lshlrev_b64 v[14:15], 13, v[14:15]
	v_lshl_add_u64 v[14:15], v[10:11], 0, v[14:15]
	v_mov_b32_e32 v13, v223
	v_fma_f32 v14, v8, v23, v0
	v_fmac_f32_e32 v14, v6, v16
	v_fma_f32 v15, v9, v24, v1
	v_fmac_f32_e32 v14, v2, v20
	v_fmac_f32_e32 v15, v7, v19
	v_fmac_f32_e32 v15, v3, v18
	s_waitcnt vmcnt(0)
	v_lshlrev_b32_e32 v21, 16, v13
	v_fmac_f32_e32 v14, v4, v21
	v_and_b32_e32 v22, 0xffff0000, v13
	v_fmac_f32_e32 v15, v5, v22
	v_bfe_u32 v13, v14, 16, 1
	v_add3_u32 v13, v14, v13, s71
	v_bfe_u32 v14, v15, 16, 1
	v_lshrrev_b32_e32 v13, 16, v13
	v_add3_u32 v14, v15, v14, s71
	v_and_or_b32 v23, v14, s81, v13
	v_or_b32_e32 v14, 12, v12
	v_ashrrev_i32_e32 v15, 31, v14
	v_lshl_add_u64 v[14:15], s[20:21], 0, v[14:15]
	v_lshlrev_b64 v[14:15], 13, v[14:15]
	v_lshl_add_u64 v[14:15], v[10:11], 0, v[14:15]
	v_mov_b32_e32 v13, v224
	v_fma_f32 v15, v8, v16, v0
	v_fmac_f32_e32 v15, v6, v20
	v_fma_f32 v16, v9, v19, v1
	v_fmac_f32_e32 v15, v2, v21
	v_fmac_f32_e32 v16, v7, v18
	v_fmac_f32_e32 v16, v3, v22
	v_fma_f32 v18, v9, v18, v1
	v_fmac_f32_e32 v18, v7, v22
	s_waitcnt vmcnt(0)
; DEV unsigned pack2(float a, float b) { return (unsigned)f2bf(a) | ((unsigned)f2bf(b) << 16); }
; DEV float lo2f(unsigned v) { return __uint_as_float(v << 16); }
; DEV float hi2f(unsigned v) { return __uint_as_float(v & 0xffff0000u); }
; DEV f32x4 mfma16(bf16x8 a, bf16x8 b, f32x4 c) { return __builtin_amdgcn_mfma_f32_16x16x32_bf16(a, b, c, 0, 0, 0); }
; PHASE void lru_phase(const Params& p, int layer, const u16* __restrict__ GC, u16* __restrict__ OC, float* __restrict__ LA, ...
;     ...
; #pragma unroll
;       for (int i = 0; i < 16; ++i) {
;         int tt = t0 + tg * 16 + i;
;         unsigned cur = *(const unsigned*)(GC + (base + tt) * 4096 + ch);
;         float y0 = b0 + w0[0] * lo2f(win[0]) + w0[1] * lo2f(win[1]) + w0[2] * lo2f(win[2]) + w0[3] * lo2f(cur);
;         float y1 = b1 + w1[0] * hi2f(win[0]) + w1[1] * hi2f(win[1]) + w1[2] * hi2f(win[2]) + w1[3] * hi2f(cur);
;         *(unsigned*)(sX + (tg * 16 + i) * 136 + 2 * cp) = pack2(y0, y1);
;         win[0] = win[1]; win[1] = win[2]; win[2] = cur;
;       }
;     ...
; #pragma unroll
;       for (int ks = 0; ks < 4; ++ks) {
;         bf16x8 a[4];
; #pragma unroll
;         for (int mi = 0; mi < 4; ++mi) a[mi] = *(const bf16x8*)(sX + (mi * 16 + fr) * 136 + ks * 32 + fq * 8);
; #pragma unroll
;         for (int ni = 0; ni < 2; ++ni) {
;           bf16x8 bR = *(const bf16x8*)(wla + (ni * 16 + fr) * 128 + ks * 32 + fq * 8);
;           bf16x8 bG = *(const bf16x8*)(wlx + (ni * 16 + fr) * 128 + ks * 32 + fq * 8);
; #pragma unroll
;           for (int mi = 0; mi < 4; ++mi) {
;             aR[mi][ni] = mfma16(a[mi], bR, aR[mi][ni]);
;             aG[mi][ni] = mfma16(a[mi], bG, aG[mi][ni]);
;           }
;         }
	v_lshlrev_b32_e32 v14, 16, v13
	v_fmac_f32_e32 v15, v4, v14
	v_and_b32_e32 v13, 0xffff0000, v13
	v_fmac_f32_e32 v16, v5, v13
	v_bfe_u32 v19, v15, 16, 1
	v_add3_u32 v15, v15, v19, s71
	v_bfe_u32 v19, v16, 16, 1
	v_lshrrev_b32_e32 v15, 16, v15
	v_add3_u32 v16, v16, v19, s71
	v_and_or_b32 v15, v16, s81, v15
	v_or_b32_e32 v16, 13, v12
	ds_write2_b32 v17, v23, v15 offset0:168 offset1:236
	v_ashrrev_i32_e32 v17, 31, v16
	v_lshl_add_u64 v[16:17], s[20:21], 0, v[16:17]
	v_lshlrev_b64 v[16:17], 13, v[16:17]
	v_lshl_add_u64 v[16:17], v[10:11], 0, v[16:17]
	v_mov_b32_e32 v15, v225
	v_fma_f32 v17, v8, v20, v0
	v_fmac_f32_e32 v17, v6, v21
	v_fmac_f32_e32 v17, v2, v14
	v_fmac_f32_e32 v18, v3, v13
	s_waitcnt vmcnt(0)
	v_lshlrev_b32_e32 v16, 16, v15
	v_fmac_f32_e32 v17, v4, v16
	v_and_b32_e32 v15, 0xffff0000, v15
	v_fmac_f32_e32 v18, v5, v15
	v_bfe_u32 v19, v17, 16, 1
	v_add3_u32 v17, v17, v19, s71
	v_bfe_u32 v19, v18, 16, 1
	v_lshrrev_b32_e32 v17, 16, v17
	v_add3_u32 v18, v18, v19, s71
	v_and_or_b32 v20, v18, s81, v17
	v_or_b32_e32 v18, 14, v12
	v_ashrrev_i32_e32 v19, 31, v18
	v_lshl_add_u64 v[18:19], s[20:21], 0, v[18:19]
	v_lshlrev_b64 v[18:19], 13, v[18:19]
	v_lshl_add_u64 v[18:19], v[10:11], 0, v[18:19]
	v_mov_b32_e32 v17, v226
	v_fma_f32 v19, v8, v21, v0
	v_fmac_f32_e32 v19, v6, v14
	v_fma_f32 v21, v9, v22, v1
	v_fmac_f32_e32 v19, v2, v16
	v_fmac_f32_e32 v21, v7, v13
	v_fmac_f32_e32 v21, v3, v15
	v_fma_f32 v0, v8, v14, v0
	v_fmac_f32_e32 v0, v6, v16
	v_fmac_f32_e32 v1, v9, v13
	v_fmac_f32_e32 v1, v7, v15
	s_waitcnt vmcnt(0)
	v_lshlrev_b32_e32 v18, 16, v17
	v_fmac_f32_e32 v19, v4, v18
	v_and_b32_e32 v17, 0xffff0000, v17
	v_fmac_f32_e32 v21, v5, v17
	v_bfe_u32 v22, v19, 16, 1
	v_add3_u32 v19, v19, v22, s71
	v_bfe_u32 v22, v21, 16, 1
	v_lshrrev_b32_e32 v19, 16, v19
	v_add3_u32 v21, v21, v22, s71
	v_and_or_b32 v19, v21, s81, v19
	v_add_u32_e32 v21, 0xc00, v134
	ds_write2_b32 v21, v20, v19 offset0:48 offset1:116
	v_or_b32_e32 v20, 15, v12
	v_ashrrev_i32_e32 v21, 31, v20
	v_lshl_add_u64 v[20:21], s[20:21], 0, v[20:21]
	v_lshlrev_b64 v[20:21], 13, v[20:21]
	v_lshl_add_u64 v[10:11], v[10:11], 0, v[20:21]
	v_mov_b32_e32 v10, v227
	v_fmac_f32_e32 v0, v2, v18
	v_fmac_f32_e32 v1, v3, v17
	v_lshl_add_u64 v[20:21], v[68:69], 0, s[24:25]
	v_lshl_add_u64 v[32:33], v[20:21], 0, v[104:105]
	v_lshl_add_u64 v[110:111], v[20:21], 0, v[106:107]
	s_mov_b32 s25, 0xbfb8aa3b
	s_mov_b32 s24, 0x7f800000
	s_waitcnt vmcnt(0)
	v_lshlrev_b32_e32 v2, 16, v10
	v_fmac_f32_e32 v0, v4, v2
	v_and_b32_e32 v2, 0xffff0000, v10
	v_fmac_f32_e32 v1, v5, v2
	v_bfe_u32 v2, v0, 16, 1
	v_add3_u32 v0, v0, v2, s71
	v_bfe_u32 v2, v1, 16, 1
	v_lshrrev_b32_e32 v0, 16, v0
	v_add3_u32 v1, v1, v2, s71
	v_and_or_b32 v0, v1, s81, v0
	ds_write_b32 v134, v0 offset:3808
	s_waitcnt lgkmcnt(0)
	s_barrier
	ds_read_b128 v[0:3], v135
	ds_read_b128 v[8:11], v135 offset:4352
	ds_read_b128 v[16:19], v135 offset:8704
	ds_read_b128 v[24:27], v135 offset:13056
	global_load_dwordx4 v[4:7], v[32:33], off
	global_load_dwordx4 v[12:15], v[34:35], off
	global_load_dwordx4 v[20:23], v[110:111], off
	global_load_dwordx4 v[162:165], v[108:109], off
	s_waitcnt vmcnt(3) lgkmcnt(3)
	v_mfma_f32_16x16x32_bf16 v[36:39], v[0:3], v[4:7], 0
	s_waitcnt vmcnt(2)
	v_mfma_f32_16x16x32_bf16 v[40:43], v[0:3], v[12:15], 0
	s_waitcnt lgkmcnt(2)
	v_mfma_f32_16x16x32_bf16 v[44:47], v[8:11], v[4:7], 0
	v_mfma_f32_16x16x32_bf16 v[48:51], v[8:11], v[12:15], 0
	s_waitcnt lgkmcnt(1)
	v_mfma_f32_16x16x32_bf16 v[52:55], v[16:19], v[4:7], 0
	v_mfma_f32_16x16x32_bf16 v[56:59], v[16:19], v[12:15], 0
	s_waitcnt lgkmcnt(0)
	v_mfma_f32_16x16x32_bf16 v[60:63], v[24:27], v[4:7], 0
	v_mfma_f32_16x16x32_bf16 v[158:161], v[24:27], v[12:15], 0
	s_waitcnt vmcnt(1)
	v_mfma_f32_16x16x32_bf16 v[28:31], v[0:3], v[20:23], 0
	s_waitcnt vmcnt(0)
	v_mfma_f32_16x16x32_bf16 v[0:3], v[0:3], v[162:165], 0
	v_mfma_f32_16x16x32_bf16 v[4:7], v[8:11], v[20:23], 0
	v_mfma_f32_16x16x32_bf16 v[8:11], v[8:11], v[162:165], 0
	v_mfma_f32_16x16x32_bf16 v[12:15], v[16:19], v[20:23], 0
	v_mfma_f32_16x16x32_bf16 v[16:19], v[16:19], v[162:165], 0
	v_mfma_f32_16x16x32_bf16 v[20:23], v[24:27], v[20:23], 0
	v_mfma_f32_16x16x32_bf16 v[24:27], v[24:27], v[162:165], 0
	ds_read_b128 v[162:165], v135 offset:64
	ds_read_b128 v[166:169], v135 offset:4416
	ds_read_b128 v[170:173], v135 offset:8768
	ds_read_b128 v[174:177], v135 offset:13120
	global_load_dwordx4 v[186:189], v[32:33], off offset:64
	global_load_dwordx4 v[192:195], v[34:35], off offset:64
	s_waitcnt vmcnt(1) lgkmcnt(3)
	v_mfma_f32_16x16x32_bf16 v[36:39], v[162:165], v[186:189], v[36:39]
	s_waitcnt vmcnt(0)
	v_mfma_f32_16x16x32_bf16 v[40:43], v[162:165], v[192:195], v[40:43]
	s_waitcnt lgkmcnt(2)
	v_mfma_f32_16x16x32_bf16 v[44:47], v[166:169], v[186:189], v[44:47]
	v_mfma_f32_16x16x32_bf16 v[48:51], v[166:169], v[192:195], v[48:51]
	s_waitcnt lgkmcnt(1)
	v_mfma_f32_16x16x32_bf16 v[52:55], v[170:173], v[186:189], v[52:55]
	v_mfma_f32_16x16x32_bf16 v[56:59], v[170:173], v[192:195], v[56:59]
	s_waitcnt lgkmcnt(0)
	v_mfma_f32_16x16x32_bf16 v[60:63], v[174:177], v[186:189], v[60:63]
	v_mfma_f32_16x16x32_bf16 v[158:161], v[174:177], v[192:195], v[158:161]
	global_load_dwordx4 v[186:189], v[110:111], off offset:64
	global_load_dwordx4 v[192:195], v[108:109], off offset:64
	s_waitcnt vmcnt(1)
	v_mfma_f32_16x16x32_bf16 v[28:31], v[162:165], v[186:189], v[28:31]
	s_waitcnt vmcnt(0)
; DEV float sigmoidf_(float x) { return 1.f / (1.f + __expf(-x)); }
; DEV f32x4 mfma16(bf16x8 a, bf16x8 b, f32x4 c) { return __builtin_amdgcn_mfma_f32_16x16x32_bf16(a, b, c, 0, 0, 0); }
; PHASE void lru_phase(const Params& p, int layer, const u16* __restrict__ GC, u16* __restrict__ OC, float* __restrict__ LA, ...
;     ...
; #pragma unroll
;       for (int ks = 0; ks < 4; ++ks) {
;         bf16x8 a[4];
; #pragma unroll
;         for (int mi = 0; mi < 4; ++mi) a[mi] = *(const bf16x8*)(sX + (mi * 16 + fr) * 136 + ks * 32 + fq * 8);
; #pragma unroll
;         for (int ni = 0; ni < 2; ++ni) {
;           bf16x8 bR = *(const bf16x8*)(wla + (ni * 16 + fr) * 128 + ks * 32 + fq * 8);
;           bf16x8 bG = *(const bf16x8*)(wlx + (ni * 16 + fr) * 128 + ks * 32 + fq * 8);
; #pragma unroll
;           for (int mi = 0; mi < 4; ++mi) {
;             aR[mi][ni] = mfma16(a[mi], bR, aR[mi][ni]);
;             aG[mi][ni] = mfma16(a[mi], bG, aG[mi][ni]);
;           }
;         }
;       }
; #pragma unroll
;       for (int ni = 0; ni < 2; ++ni) {
;         const int col = wid * 32 + ni * 16 + fr;
;         const float bba = ba[ch0 + col], bbx = bx[ch0 + col];
;         const float c8 = 8.f * log1pf(expf(-lam[ch0 + col]));
; #pragma unroll
;         for (int mi = 0; mi < 4; ++mi)
; #pragma unroll
;           for (int j = 0; j < 4; ++j) {
;             const int t = mi * 16 + fq * 4 + j;
;             const float rr = sigmoidf_(aR[mi][ni][j] + bba);
;             const float gg = sigmoidf_(aG[mi][ni][j] + bbx);
	v_mfma_f32_16x16x32_bf16 v[0:3], v[162:165], v[192:195], v[0:3]
	v_mfma_f32_16x16x32_bf16 v[4:7], v[166:169], v[186:189], v[4:7]
	v_mfma_f32_16x16x32_bf16 v[8:11], v[166:169], v[192:195], v[8:11]
	v_mfma_f32_16x16x32_bf16 v[12:15], v[170:173], v[186:189], v[12:15]
	v_mfma_f32_16x16x32_bf16 v[16:19], v[170:173], v[192:195], v[16:19]
	v_mfma_f32_16x16x32_bf16 v[20:23], v[174:177], v[186:189], v[20:23]
	v_mfma_f32_16x16x32_bf16 v[24:27], v[174:177], v[192:195], v[24:27]
	ds_read_b128 v[162:165], v135 offset:128
	ds_read_b128 v[166:169], v135 offset:4480
	ds_read_b128 v[170:173], v135 offset:8832
	ds_read_b128 v[174:177], v135 offset:13184
	global_load_dwordx4 v[186:189], v[32:33], off offset:128
	global_load_dwordx4 v[192:195], v[34:35], off offset:128
	s_waitcnt vmcnt(1) lgkmcnt(1)
	v_mfma_f32_16x16x32_bf16 v[196:199], v[170:173], v[186:189], v[52:55]
	s_waitcnt vmcnt(0)
	v_mfma_f32_16x16x32_bf16 v[200:203], v[170:173], v[192:195], v[56:59]
	s_nop 0
	global_load_dwordx4 v[52:55], v[110:111], off offset:128
	s_nop 0
	global_load_dwordx4 v[56:59], v[108:109], off offset:128
	v_mfma_f32_16x16x32_bf16 v[36:39], v[162:165], v[186:189], v[36:39]
	v_mfma_f32_16x16x32_bf16 v[40:43], v[162:165], v[192:195], v[40:43]
	v_mfma_f32_16x16x32_bf16 v[44:47], v[166:169], v[186:189], v[44:47]
	v_mfma_f32_16x16x32_bf16 v[48:51], v[166:169], v[192:195], v[48:51]
	s_waitcnt lgkmcnt(0)
	v_mfma_f32_16x16x32_bf16 v[186:189], v[174:177], v[186:189], v[60:63]
	v_mfma_f32_16x16x32_bf16 v[158:161], v[174:177], v[192:195], v[158:161]
	s_waitcnt vmcnt(1)
	v_mfma_f32_16x16x32_bf16 v[28:31], v[162:165], v[52:55], v[28:31]
	s_waitcnt vmcnt(0)
	v_mfma_f32_16x16x32_bf16 v[0:3], v[162:165], v[56:59], v[0:3]
	v_mfma_f32_16x16x32_bf16 v[4:7], v[166:169], v[52:55], v[4:7]
	v_mfma_f32_16x16x32_bf16 v[8:11], v[166:169], v[56:59], v[8:11]
	v_mfma_f32_16x16x32_bf16 v[12:15], v[170:173], v[52:55], v[12:15]
	v_mfma_f32_16x16x32_bf16 v[162:165], v[170:173], v[56:59], v[16:19]
	v_mfma_f32_16x16x32_bf16 v[166:169], v[174:177], v[52:55], v[20:23]
	v_mfma_f32_16x16x32_bf16 v[170:173], v[174:177], v[56:59], v[24:27]
	s_nop 0
	ds_read_b128 v[16:19], v135 offset:192
	ds_read_b128 v[174:177], v135 offset:4544
	ds_read_b128 v[192:195], v135 offset:8896
	ds_read_b128 v[204:207], v135 offset:13248
	global_load_dwordx4 v[20:23], v[32:33], off offset:192
	global_load_dwordx4 v[24:27], v[34:35], off offset:192
	s_waitcnt vmcnt(0) lgkmcnt(0)
	v_mfma_f32_16x16x32_bf16 v[32:35], v[204:207], v[24:27], v[158:161]
	global_load_dwordx4 v[110:113], v[110:111], off offset:192
	s_nop 1
	global_load_dwordx4 v[158:161], v[108:109], off offset:192
	v_add_u32_e32 v108, s29, v115
	v_ashrrev_i32_e32 v109, 31, v108
	v_lshlrev_b64 v[108:109], 2, v[108:109]
	v_mfma_f32_16x16x32_bf16 v[60:63], v[16:19], v[20:23], v[36:39]
	v_mfma_f32_16x16x32_bf16 v[52:55], v[174:177], v[20:23], v[44:47]
	v_mfma_f32_16x16x32_bf16 v[44:47], v[192:195], v[20:23], v[196:199]
	v_mfma_f32_16x16x32_bf16 v[36:39], v[204:207], v[20:23], v[186:189]
	s_waitcnt vmcnt(1)
	v_mfma_f32_16x16x32_bf16 v[28:31], v[16:19], v[110:113], v[28:31]
	v_mfma_f32_16x16x32_bf16 v[20:23], v[174:177], v[110:113], v[4:7]
	v_mfma_f32_16x16x32_bf16 v[12:15], v[192:195], v[110:113], v[12:15]
	v_mfma_f32_16x16x32_bf16 v[4:7], v[204:207], v[110:113], v[166:169]
	v_lshl_add_u64 v[110:111], s[12:13], 0, v[108:109]
	v_lshl_add_u64 v[112:113], s[14:15], 0, v[108:109]
	v_lshl_add_u64 v[108:109], s[16:17], 0, v[108:109]
	global_load_dword v154, v[108:109], off
	global_load_dword v107, v[110:111], off
	v_mfma_f32_16x16x32_bf16 v[56:59], v[16:19], v[24:27], v[40:43]
	v_mov_b32_e32 v167, 0x7f800000
	global_load_dword v105, v[112:113], off
	s_waitcnt vmcnt(2)
	v_mul_f32_e32 v155, 0xbfb8aa3b, v154
	v_mfma_f32_16x16x32_bf16 v[48:51], v[174:177], v[24:27], v[48:51]
	v_fma_f32 v156, v154, s25, -v155
	v_fmac_f32_e32 v156, 0xb2a5705f, v154
	v_cmp_nlt_f32_e32 vcc, s26, v154
	v_mfma_f32_16x16x32_bf16 v[40:43], v[192:195], v[24:27], v[200:203]
	s_waitcnt vmcnt(1)
	v_add_f32_e32 v60, v60, v107
	v_mul_f32_e32 v60, 0xbfb8aa3b, v60
	v_exp_f32_e32 v60, v60
	v_mfma_f32_16x16x32_bf16 v[24:27], v[16:19], v[158:161], v[0:3]
	s_waitcnt vmcnt(0)
	v_add_f32_e32 v56, v56, v105
	v_mul_f32_e32 v56, 0xbfb8aa3b, v56
	v_add_f32_e32 v60, 1.0, v60
	v_mfma_f32_16x16x32_bf16 v[16:19], v[174:177], v[158:161], v[8:11]
	v_exp_f32_e32 v56, v56
	v_add_f32_e32 v57, v57, v105
	v_mul_f32_e32 v57, 0xbfb8aa3b, v57
	v_mfma_f32_16x16x32_bf16 v[8:11], v[192:195], v[158:161], v[162:165]
	v_add_f32_e32 v56, 1.0, v56
	v_exp_f32_e32 v57, v57
	v_add_f32_e32 v52, v52, v107
	v_mfma_f32_16x16x32_bf16 v[0:3], v[204:207], v[158:161], v[170:173]
	v_rndne_f32_e32 v158, v155
	v_sub_f32_e32 v155, v155, v158
	v_add_f32_e32 v155, v155, v156
	v_exp_f32_e32 v155, v155
	v_cvt_i32_f32_e32 v156, v158
	v_add_f32_e32 v57, 1.0, v57
	v_mul_f32_e32 v52, 0xbfb8aa3b, v52
	v_exp_f32_e32 v52, v52
	v_ldexp_f32 v155, v155, v156
	v_cndmask_b32_e32 v155, 0, v155, vcc
	v_cmp_ngt_f32_e32 vcc, s27, v154
	v_add_f32_e32 v52, 1.0, v52
	v_add_f32_e32 v48, v48, v105
	v_cndmask_b32_e32 v156, v167, v155, vcc
	v_add_f32_e32 v158, 1.0, v156
	v_add_f32_e32 v154, -1.0, v158
	v_sub_f32_e32 v155, v154, v158
	v_add_f32_e32 v155, 1.0, v155
	v_sub_f32_e32 v154, v156, v154
	v_add_f32_e32 v159, v154, v155
	v_frexp_mant_f32_e32 v154, v158
	v_cmp_gt_f32_e32 vcc, s35, v154
	v_cvt_f64_f32_e32 v[154:155], v158
	v_frexp_exp_i32_f64_e32 v154, v[154:155]
	v_subbrev_co_u32_e32 v154, vcc, 0, v154, vcc
	v_sub_u32_e32 v155, 0, v154
	v_ldexp_f32 v158, v158, v155
	v_ldexp_f32 v155, v159, v155
	v_add_f32_e32 v159, -1.0, v158
	v_add_f32_e32 v160, 1.0, v159
	v_sub_f32_e32 v160, v158, v160
; DEV float bf2f(u16 h) { return __uint_as_float(((unsigned)h) << 16); }
; DEV float sigmoidf_(float x) { return 1.f / (1.f + __expf(-x)); }
; PHASE void lru_phase(const Params& p, int layer, const u16* __restrict__ GC, u16* __restrict__ OC, float* __restrict__ LA, ...
;     ...
;         const float c8 = 8.f * log1pf(expf(-lam[ch0 + col]));
; #pragma unroll
;         for (int mi = 0; mi < 4; ++mi)
; #pragma unroll
;           for (int j = 0; j < 4; ++j) {
;             const int t = mi * 16 + fq * 4 + j;
;             const float rr = sigmoidf_(aR[mi][ni][j] + bba);
;             const float gg = sigmoidf_(aG[mi][ni][j] + bbx);
;             const float xv = bf2f(sX[t * 136 + col]);
;             const float la = -c8 * rr;
;             const float l2 = la + la;
;             const float e1 = la * (1.f + la * (0.5f + la * (0.16666667f + la * (0.041666668f + la * (0.0083333338f + la * 0.0013888889f)))));
;             const float e2 = l2 * (1.f + l2 * (0.5f + l2 * (0.16666667f + l2 * (0.041666668f + l2 * (0.0083333338f + l2 * (0.0013888889f + l2 * 0.0001984127f))))));
;             sR[t * 128 + col] = f2bf(-e1);
;             sG[t * 128 + col] = f2bf(__builtin_amdgcn_sqrtf(fmaxf(-e2, 0.f)) * gg * xv);
	v_add_f32_e32 v160, v155, v160
	v_add_f32_e32 v161, v159, v160
	v_sub_f32_e32 v159, v159, v161
	v_add_f32_e32 v159, v160, v159
	v_add_f32_e32 v160, 1.0, v158
	v_add_f32_e32 v162, -1.0, v160
	v_sub_f32_e32 v158, v158, v162
	v_add_f32_e32 v155, v155, v158
	v_add_f32_e32 v158, v160, v155
	v_sub_f32_e32 v160, v160, v158
	v_add_f32_e32 v155, v155, v160
	v_rcp_f32_e32 v160, v158
	v_cvt_f32_i32_e32 v154, v154
	v_cmp_neq_f32_e32 vcc, s24, v156
	v_mul_f32_e32 v48, 0xbfb8aa3b, v48
	v_mul_f32_e32 v162, v161, v160
	v_mul_f32_e32 v163, v158, v162
	v_fma_f32 v164, v162, v158, -v163
	v_fmac_f32_e32 v164, v162, v155
	v_add_f32_e32 v165, v163, v164
	v_sub_f32_e32 v166, v161, v165
	v_sub_f32_e32 v161, v161, v166
	v_sub_f32_e32 v163, v165, v163
	v_sub_f32_e32 v161, v161, v165
	v_add_f32_e32 v159, v159, v161
	v_sub_f32_e32 v161, v163, v164
	v_add_f32_e32 v159, v161, v159
	v_add_f32_e32 v161, v166, v159
	v_mul_f32_e32 v163, v160, v161
	v_mul_f32_e32 v164, v158, v163
	v_fma_f32 v158, v163, v158, -v164
	v_fmac_f32_e32 v158, v163, v155
	v_sub_f32_e32 v155, v166, v161
	v_add_f32_e32 v155, v159, v155
	v_add_f32_e32 v159, v164, v158
	v_sub_f32_e32 v165, v161, v159
	v_sub_f32_e32 v161, v161, v165
	v_sub_f32_e32 v164, v159, v164
	v_sub_f32_e32 v159, v161, v159
	v_add_f32_e32 v155, v155, v159
	v_sub_f32_e32 v158, v164, v158
	v_add_f32_e32 v155, v158, v155
	v_add_f32_e32 v158, v162, v163
	v_add_f32_e32 v155, v165, v155
	v_sub_f32_e32 v159, v158, v162
	v_mul_f32_e32 v155, v160, v155
	v_sub_f32_e32 v159, v163, v159
	v_add_f32_e32 v155, v159, v155
	v_mul_f32_e32 v162, 0x3f317218, v154
	v_add_f32_e32 v159, v158, v155
	v_fma_f32 v163, v154, s36, -v162
	v_mul_f32_e32 v160, v159, v159
	v_mov_b32_e32 v164, 0x3ecc95a3
	v_fmac_f32_e32 v163, 0xb102e308, v154
	v_sub_f32_e32 v154, v159, v158
	v_fmamk_f32 v161, v160, 0x3e9b6dac, v164
	v_sub_f32_e32 v154, v155, v154
	v_add_f32_e32 v155, v162, v163
	v_fmaak_f32 v161, v160, v161, 0x3f2aaada
	v_sub_f32_e32 v158, v155, v162
	v_ldexp_f32 v162, v159, 1
	v_mul_f32_e32 v159, v159, v160
	v_mul_f32_e32 v159, v159, v161
	v_add_f32_e32 v160, v162, v159
	v_sub_f32_e32 v161, v160, v162
	v_ldexp_f32 v154, v154, 1
	v_sub_f32_e32 v159, v159, v161
	v_add_f32_e32 v154, v154, v159
	v_add_f32_e32 v159, v160, v154
	v_sub_f32_e32 v160, v159, v160
	v_sub_f32_e32 v154, v154, v160
	v_add_f32_e32 v160, v155, v159
	v_sub_f32_e32 v161, v160, v155
	v_sub_f32_e32 v162, v160, v161
	v_sub_f32_e32 v158, v163, v158
	v_sub_f32_e32 v155, v155, v162
	v_sub_f32_e32 v159, v159, v161
	v_add_f32_e32 v155, v159, v155
	v_add_f32_e32 v159, v158, v154
	v_sub_f32_e32 v161, v159, v158
	v_sub_f32_e32 v162, v159, v161
	v_sub_f32_e32 v158, v158, v162
	v_sub_f32_e32 v154, v154, v161
	v_add_f32_e32 v155, v159, v155
	v_add_f32_e32 v154, v154, v158
	v_add_f32_e32 v158, v160, v155
	v_sub_f32_e32 v159, v158, v160
	v_sub_f32_e32 v155, v155, v159
	v_add_f32_e32 v154, v154, v155
	v_add_f32_e32 v154, v158, v154
	v_cndmask_b32_e32 v154, v167, v154, vcc
	v_cmp_lt_f32_e64 vcc, |v156|, s37
	v_div_scale_f32 v155, s[0:1], v60, v60, 1.0
	s_nop 0
	v_cndmask_b32_e32 v154, v154, v156, vcc
	v_rcp_f32_e32 v156, v155
	v_mul_f32_e32 v154, 0xc1000000, v154
	v_exp_f32_e32 v48, v48
	v_add_f32_e32 v49, v49, v105
	v_fma_f32 v158, -v155, v156, 1.0
	v_fmac_f32_e32 v156, v158, v156
	v_div_scale_f32 v158, vcc, 1.0, v60, 1.0
	v_mul_f32_e32 v159, v158, v156
	v_fma_f32 v160, -v155, v159, v158
	v_fmac_f32_e32 v159, v160, v156
	v_fma_f32 v155, -v155, v159, v158
	v_div_fmas_f32 v155, v155, v156, v159
	v_div_fixup_f32 v60, v155, v60, 1.0
	v_div_scale_f32 v155, s[0:1], v56, v56, 1.0
	v_rcp_f32_e32 v156, v155
	v_mul_f32_e32 v60, v60, v154
	v_add_f32_e32 v48, 1.0, v48
	v_mul_f32_e32 v49, 0xbfb8aa3b, v49
	v_fma_f32 v158, -v155, v156, 1.0
	v_fmac_f32_e32 v156, v158, v156
	v_div_scale_f32 v158, vcc, 1.0, v56, 1.0
	v_mul_f32_e32 v159, v158, v156
	v_fma_f32 v160, -v155, v159, v158
	v_fmac_f32_e32 v159, v160, v156
	v_fma_f32 v155, -v155, v159, v158
	v_fmamk_f32 v158, v60, 0x3ab60b61, v181
	v_div_fmas_f32 v155, v155, v156, v159
	v_add_f32_e32 v156, v60, v60
	v_fmaak_f32 v158, v60, v158, 0x3d2aaaab
	v_fmaak_f32 v158, v60, v158, 0x3e2aaaab
	v_fmamk_f32 v159, v156, 0x39500d01, v191
	v_fma_f32 v158, v60, v158, 0.5
	v_fmaak_f32 v159, v156, v159, 0x3c088889
	v_fma_f32 v158, v60, v158, 1.0
	v_fmaak_f32 v159, v156, v159, 0x3d2aaaab
	v_fmaak_f32 v159, v156, v159, 0x3e2aaaab
	v_mul_f32_e64 v60, v60, -v158
	v_fma_f32 v159, v156, v159, 0.5
	v_bfe_u32 v158, v60, 16, 1
	v_fma_f32 v159, v156, v159, 1.0
	v_add3_u32 v60, v60, v158, s71
	v_div_fixup_f32 v56, v155, v56, 1.0
	ds_read_u16 v155, v136
	ds_write_b16_d16_hi v116, v60 offset:17408
	v_mul_f32_e64 v60, v156, -v159
	v_max_f32_e32 v60, 0, v60
	v_sqrt_f32_e32 v60, v60
	s_waitcnt lgkmcnt(1)
; DEV float bf2f(u16 h) { return __uint_as_float(((unsigned)h) << 16); }
; DEV float sigmoidf_(float x) { return 1.f / (1.f + __expf(-x)); }
; PHASE void lru_phase(const Params& p, int layer, const u16* __restrict__ GC, u16* __restrict__ OC, float* __restrict__ LA, ...
;     ...
;         for (int mi = 0; mi < 4; ++mi)
; #pragma unroll
;           for (int j = 0; j < 4; ++j) {
;             const int t = mi * 16 + fq * 4 + j;
;             const float rr = sigmoidf_(aR[mi][ni][j] + bba);
;             const float gg = sigmoidf_(aG[mi][ni][j] + bbx);
;             const float xv = bf2f(sX[t * 136 + col]);
;             const float la = -c8 * rr;
;             const float l2 = la + la;
;             const float e1 = la * (1.f + la * (0.5f + la * (0.16666667f + la * (0.041666668f + la * (0.0083333338f + la * 0.0013888889f)))));
;             const float e2 = l2 * (1.f + l2 * (0.5f + l2 * (0.16666667f + l2 * (0.041666668f + l2 * (0.0083333338f + l2 * (0.0013888889f + l2 * 0.0001984127f))))));
;             sR[t * 128 + col] = f2bf(-e1);
;             sG[t * 128 + col] = f2bf(__builtin_amdgcn_sqrtf(fmaxf(-e2, 0.f)) * gg * xv);
;           }
	v_lshlrev_b32_e32 v155, 16, v155
	v_exp_f32_e32 v49, v49
	v_add_f32_e32 v44, v44, v107
	v_mul_f32_e32 v56, v56, v60
	v_mul_f32_e32 v56, v56, v155
	v_bfe_u32 v60, v56, 16, 1
	v_add3_u32 v56, v56, v60, s71
	ds_write_b16_d16_hi v116, v56 offset:33792
	v_add_f32_e32 v56, v61, v107
	v_mul_f32_e32 v56, 0xbfb8aa3b, v56
	v_exp_f32_e32 v56, v56
	v_add_f32_e32 v49, 1.0, v49
	v_mul_f32_e32 v44, 0xbfb8aa3b, v44
	v_exp_f32_e32 v44, v44
	v_add_f32_e32 v56, 1.0, v56
	v_div_scale_f32 v60, s[0:1], v56, v56, 1.0
	v_rcp_f32_e32 v61, v60
	v_add_f32_e32 v44, 1.0, v44
	v_add_f32_e32 v40, v40, v105
	v_mul_f32_e32 v40, 0xbfb8aa3b, v40
	v_fma_f32 v155, -v60, v61, 1.0
	v_fmac_f32_e32 v61, v155, v61
	v_div_scale_f32 v155, vcc, 1.0, v56, 1.0
	v_mul_f32_e32 v156, v155, v61
	v_fma_f32 v158, -v60, v156, v155
	v_fmac_f32_e32 v156, v158, v61
	v_fma_f32 v60, -v60, v156, v155
	v_div_fmas_f32 v60, v60, v61, v156
	v_div_fixup_f32 v56, v60, v56, 1.0
	v_div_scale_f32 v60, s[0:1], v57, v57, 1.0
	v_rcp_f32_e32 v61, v60
	v_mul_f32_e32 v56, v56, v154
	v_exp_f32_e32 v40, v40
	v_add_f32_e32 v41, v41, v105
	v_fma_f32 v155, -v60, v61, 1.0
	v_fmac_f32_e32 v61, v155, v61
	v_div_scale_f32 v155, vcc, 1.0, v57, 1.0
	v_mul_f32_e32 v156, v155, v61
	v_fma_f32 v158, -v60, v156, v155
	v_fmac_f32_e32 v156, v158, v61
	v_fma_f32 v60, -v60, v156, v155
	v_fmamk_f32 v155, v56, 0x3ab60b61, v181
	v_div_fmas_f32 v60, v60, v61, v156
	v_add_f32_e32 v61, v56, v56
	v_fmaak_f32 v155, v56, v155, 0x3d2aaaab
	v_fmaak_f32 v155, v56, v155, 0x3e2aaaab
	v_fmamk_f32 v156, v61, 0x39500d01, v191
	v_fma_f32 v155, v56, v155, 0.5
	v_fmaak_f32 v156, v61, v156, 0x3c088889
	v_fma_f32 v155, v56, v155, 1.0
	v_fmaak_f32 v156, v61, v156, 0x3d2aaaab
	v_fmaak_f32 v156, v61, v156, 0x3e2aaaab
	v_mul_f32_e64 v56, v56, -v155
	v_fma_f32 v156, v61, v156, 0.5
	v_bfe_u32 v155, v56, 16, 1
	v_fma_f32 v156, v61, v156, 1.0
	v_add3_u32 v56, v56, v155, s71
	v_div_fixup_f32 v57, v60, v57, 1.0
	ds_read_u16 v60, v137
	ds_write_b16_d16_hi v117, v56 offset:17408
	v_mul_f32_e64 v56, v61, -v156
	v_max_f32_e32 v56, 0, v56
	v_sqrt_f32_e32 v56, v56
	s_waitcnt lgkmcnt(1)
	v_lshlrev_b32_e32 v60, 16, v60
	v_add_f32_e32 v40, 1.0, v40
	v_mul_f32_e32 v41, 0xbfb8aa3b, v41
	v_mul_f32_e32 v56, v57, v56
	v_mul_f32_e32 v56, v56, v60
	v_bfe_u32 v57, v56, 16, 1
	v_add3_u32 v56, v56, v57, s71
	ds_write_b16_d16_hi v117, v56 offset:33792
	v_add_f32_e32 v56, v62, v107
	v_mul_f32_e32 v56, 0xbfb8aa3b, v56
	v_exp_f32_e32 v56, v56
	v_exp_f32_e32 v41, v41
	v_add_f32_e32 v36, v36, v107
	v_mul_f32_e32 v36, 0xbfb8aa3b, v36
	v_add_f32_e32 v56, 1.0, v56
	v_div_scale_f32 v57, s[0:1], v56, v56, 1.0
	v_rcp_f32_e32 v60, v57
	v_add_f32_e32 v41, 1.0, v41
	v_exp_f32_e32 v36, v36
	v_add_f32_e32 v32, v32, v105
	v_fma_f32 v61, -v57, v60, 1.0
	v_fmac_f32_e32 v60, v61, v60
	v_div_scale_f32 v61, vcc, 1.0, v56, 1.0
	v_mul_f32_e32 v62, v61, v60
	v_fma_f32 v155, -v57, v62, v61
	v_fmac_f32_e32 v62, v155, v60
	v_fma_f32 v57, -v57, v62, v61
	v_div_fmas_f32 v57, v57, v60, v62
	v_div_fixup_f32 v56, v57, v56, 1.0
	v_add_f32_e32 v57, v58, v105
	v_mul_f32_e32 v57, 0xbfb8aa3b, v57
	v_exp_f32_e32 v57, v57
	v_mul_f32_e32 v56, v56, v154
	v_add_f32_e32 v36, 1.0, v36
	v_mul_f32_e32 v32, 0xbfb8aa3b, v32
	v_add_f32_e32 v57, 1.0, v57
	v_div_scale_f32 v58, s[0:1], v57, v57, 1.0
	v_rcp_f32_e32 v60, v58
	v_exp_f32_e32 v32, v32
	v_add_f32_e32 v33, v33, v105
	v_mul_f32_e32 v33, 0xbfb8aa3b, v33
	v_fma_f32 v61, -v58, v60, 1.0
	v_fmac_f32_e32 v60, v61, v60
	v_div_scale_f32 v61, vcc, 1.0, v57, 1.0
	v_mul_f32_e32 v62, v61, v60
	v_fma_f32 v155, -v58, v62, v61
	v_fmac_f32_e32 v62, v155, v60
	v_fma_f32 v58, -v58, v62, v61
	v_fmamk_f32 v61, v56, 0x3ab60b61, v181
	v_div_fmas_f32 v58, v58, v60, v62
	v_add_f32_e32 v60, v56, v56
	v_fmaak_f32 v61, v56, v61, 0x3d2aaaab
	v_fmaak_f32 v61, v56, v61, 0x3e2aaaab
	v_fmamk_f32 v62, v60, 0x39500d01, v191
	v_fma_f32 v61, v56, v61, 0.5
	v_fmaak_f32 v62, v60, v62, 0x3c088889
	v_fma_f32 v61, v56, v61, 1.0
	v_fmaak_f32 v62, v60, v62, 0x3d2aaaab
	v_fmaak_f32 v62, v60, v62, 0x3e2aaaab
	v_mul_f32_e64 v56, v56, -v61
	v_fma_f32 v62, v60, v62, 0.5
	v_bfe_u32 v61, v56, 16, 1
	v_fma_f32 v62, v60, v62, 1.0
	v_add3_u32 v56, v56, v61, s71
	v_div_fixup_f32 v57, v58, v57, 1.0
	ds_read_u16 v58, v137 offset:272
	ds_write_b16_d16_hi v118, v56 offset:17408
	v_mul_f32_e64 v56, v60, -v62
	v_max_f32_e32 v56, 0, v56
	v_sqrt_f32_e32 v56, v56
	s_waitcnt lgkmcnt(1)
	v_lshlrev_b32_e32 v58, 16, v58
	v_add_f32_e32 v32, 1.0, v32
	v_exp_f32_e32 v33, v33
	v_mul_f32_e32 v56, v57, v56
	v_mul_f32_e32 v56, v56, v58
	v_bfe_u32 v57, v56, 16, 1
	v_add3_u32 v56, v56, v57, s71
	ds_write_b16_d16_hi v118, v56 offset:33792
	v_add_f32_e32 v56, v63, v107
	v_mul_f32_e32 v56, 0xbfb8aa3b, v56
	v_exp_f32_e32 v56, v56
	v_add_f32_e32 v33, 1.0, v33
	v_add_f32_e32 v56, 1.0, v56
	v_div_scale_f32 v57, s[0:1], v56, v56, 1.0
	v_rcp_f32_e32 v58, v57
	s_nop 0
	v_fma_f32 v60, -v57, v58, 1.0
	v_fmac_f32_e32 v58, v60, v58
	v_div_scale_f32 v60, vcc, 1.0, v56, 1.0
	v_mul_f32_e32 v61, v60, v58
	v_fma_f32 v62, -v57, v61, v60
	v_fmac_f32_e32 v61, v62, v58
	v_fma_f32 v57, -v57, v61, v60
	v_div_fmas_f32 v57, v57, v58, v61
	v_div_fixup_f32 v56, v57, v56, 1.0
	v_add_f32_e32 v57, v59, v105
	v_mul_f32_e32 v57, 0xbfb8aa3b, v57
	v_exp_f32_e32 v57, v57
	v_mul_f32_e32 v56, v56, v154
	v_add_f32_e32 v57, 1.0, v57
	v_div_scale_f32 v58, s[0:1], v57, v57, 1.0
	v_rcp_f32_e32 v59, v58
	s_nop 0
	v_fma_f32 v60, -v58, v59, 1.0
	v_fmac_f32_e32 v59, v60, v59
	v_div_scale_f32 v60, vcc, 1.0, v57, 1.0
	v_mul_f32_e32 v61, v60, v59
	v_fma_f32 v62, -v58, v61, v60
	v_fmac_f32_e32 v61, v62, v59
	v_fma_f32 v58, -v58, v61, v60
	v_fmamk_f32 v60, v56, 0x3ab60b61, v181
	v_div_fmas_f32 v58, v58, v59, v61
	v_add_f32_e32 v59, v56, v56
	v_fmaak_f32 v60, v56, v60, 0x3d2aaaab
	v_fmaak_f32 v60, v56, v60, 0x3e2aaaab
	v_fmamk_f32 v61, v59, 0x39500d01, v191
	v_fma_f32 v60, v56, v60, 0.5
	v_fmaak_f32 v61, v59, v61, 0x3c088889
	v_fma_f32 v60, v56, v60, 1.0
	v_fmaak_f32 v61, v59, v61, 0x3d2aaaab
	v_fmaak_f32 v61, v59, v61, 0x3e2aaaab
	v_mul_f32_e64 v56, v56, -v60
	v_fma_f32 v61, v59, v61, 0.5
	v_bfe_u32 v60, v56, 16, 1
	v_fma_f32 v61, v59, v61, 1.0
	v_add3_u32 v56, v56, v60, s71
	v_div_fixup_f32 v57, v58, v57, 1.0
	ds_read_u16 v58, v137 offset:544
	ds_write_b16_d16_hi v119, v56 offset:17408
	v_mul_f32_e64 v56, v59, -v61
	v_max_f32_e32 v56, 0, v56
	v_sqrt_f32_e32 v56, v56
	s_waitcnt lgkmcnt(1)
; DEV float bf2f(u16 h) { return __uint_as_float(((unsigned)h) << 16); }
; DEV float sigmoidf_(float x) { return 1.f / (1.f + __expf(-x)); }
; PHASE void lru_phase(const Params& p, int layer, const u16* __restrict__ GC, u16* __restrict__ OC, float* __restrict__ LA, ...
;     ...
;         for (int mi = 0; mi < 4; ++mi)
; #pragma unroll
;           for (int j = 0; j < 4; ++j) {
;             const int t = mi * 16 + fq * 4 + j;
;             const float rr = sigmoidf_(aR[mi][ni][j] + bba);
;             const float gg = sigmoidf_(aG[mi][ni][j] + bbx);
;             const float xv = bf2f(sX[t * 136 + col]);
;             const float la = -c8 * rr;
;             const float l2 = la + la;
;             const float e1 = la * (1.f + la * (0.5f + la * (0.16666667f + la * (0.041666668f + la * (0.0083333338f + la * 0.0013888889f)))));
;             const float e2 = l2 * (1.f + l2 * (0.5f + l2 * (0.16666667f + l2 * (0.041666668f + l2 * (0.0083333338f + l2 * (0.0013888889f + l2 * 0.0001984127f))))));
;             sR[t * 128 + col] = f2bf(-e1);
;             sG[t * 128 + col] = f2bf(__builtin_amdgcn_sqrtf(fmaxf(-e2, 0.f)) * gg * xv);
;           }
	v_lshlrev_b32_e32 v58, 16, v58
	v_mul_f32_e32 v56, v57, v56
	v_mul_f32_e32 v56, v56, v58
	v_bfe_u32 v57, v56, 16, 1
	v_add3_u32 v56, v56, v57, s71
	ds_write_b16_d16_hi v119, v56 offset:33792
	v_div_scale_f32 v56, s[0:1], v52, v52, 1.0
	v_rcp_f32_e32 v57, v56
	s_nop 0
	v_fma_f32 v58, -v56, v57, 1.0
	v_fmac_f32_e32 v57, v58, v57
	v_div_scale_f32 v58, vcc, 1.0, v52, 1.0
	v_mul_f32_e32 v59, v58, v57
	v_fma_f32 v60, -v56, v59, v58
	v_fmac_f32_e32 v59, v60, v57
	v_fma_f32 v56, -v56, v59, v58
	v_div_fmas_f32 v56, v56, v57, v59
	v_div_fixup_f32 v52, v56, v52, 1.0
	v_div_scale_f32 v56, s[0:1], v48, v48, 1.0
	v_rcp_f32_e32 v57, v56
	v_mul_f32_e32 v52, v52, v154
	v_fma_f32 v58, -v56, v57, 1.0
	v_fmac_f32_e32 v57, v58, v57
	v_div_scale_f32 v58, vcc, 1.0, v48, 1.0
	v_mul_f32_e32 v59, v58, v57
	v_fma_f32 v60, -v56, v59, v58
	v_fmac_f32_e32 v59, v60, v57
	v_fma_f32 v56, -v56, v59, v58
	v_fmamk_f32 v58, v52, 0x3ab60b61, v181
	v_div_fmas_f32 v56, v56, v57, v59
	v_add_f32_e32 v57, v52, v52
	v_fmaak_f32 v58, v52, v58, 0x3d2aaaab
	v_fmaak_f32 v58, v52, v58, 0x3e2aaaab
	v_fmamk_f32 v59, v57, 0x39500d01, v191
	v_fma_f32 v58, v52, v58, 0.5
	v_fmaak_f32 v59, v57, v59, 0x3c088889
	v_fma_f32 v58, v52, v58, 1.0
	v_fmaak_f32 v59, v57, v59, 0x3d2aaaab
	v_fmaak_f32 v59, v57, v59, 0x3e2aaaab
	v_mul_f32_e64 v52, v52, -v58
	v_fma_f32 v59, v57, v59, 0.5
	v_bfe_u32 v58, v52, 16, 1
	v_fma_f32 v59, v57, v59, 1.0
	v_add3_u32 v52, v52, v58, s71
	v_div_fixup_f32 v48, v56, v48, 1.0
	ds_read_u16 v56, v137 offset:4080
	ds_write_b16_d16_hi v120, v52 offset:17408
	v_mul_f32_e64 v52, v57, -v59
	v_max_f32_e32 v52, 0, v52
	v_sqrt_f32_e32 v52, v52
	s_waitcnt lgkmcnt(1)
	v_lshlrev_b32_e32 v56, 16, v56
	v_mul_f32_e32 v48, v48, v52
	v_mul_f32_e32 v48, v48, v56
	v_bfe_u32 v52, v48, 16, 1
	v_add3_u32 v48, v48, v52, s71
	ds_write_b16_d16_hi v120, v48 offset:33792
	v_add_f32_e32 v48, v53, v107
	v_mul_f32_e32 v48, 0xbfb8aa3b, v48
	v_exp_f32_e32 v48, v48
	s_nop 0
	v_add_f32_e32 v48, 1.0, v48
	v_div_scale_f32 v52, s[0:1], v48, v48, 1.0
	v_rcp_f32_e32 v53, v52
	s_nop 0
	v_fma_f32 v56, -v52, v53, 1.0
	v_fmac_f32_e32 v53, v56, v53
	v_div_scale_f32 v56, vcc, 1.0, v48, 1.0
	v_mul_f32_e32 v57, v56, v53
	v_fma_f32 v58, -v52, v57, v56
	v_fmac_f32_e32 v57, v58, v53
	v_fma_f32 v52, -v52, v57, v56
	v_div_fmas_f32 v52, v52, v53, v57
	v_div_fixup_f32 v48, v52, v48, 1.0
	v_div_scale_f32 v52, s[0:1], v49, v49, 1.0
	v_rcp_f32_e32 v53, v52
	v_mul_f32_e32 v48, v48, v154
	v_fma_f32 v56, -v52, v53, 1.0
	v_fmac_f32_e32 v53, v56, v53
	v_div_scale_f32 v56, vcc, 1.0, v49, 1.0
	v_mul_f32_e32 v57, v56, v53
	v_fma_f32 v58, -v52, v57, v56
	v_fmac_f32_e32 v57, v58, v53
	v_fma_f32 v52, -v52, v57, v56
	v_fmamk_f32 v56, v48, 0x3ab60b61, v181
	v_div_fmas_f32 v52, v52, v53, v57
	v_add_f32_e32 v53, v48, v48
	v_fmaak_f32 v56, v48, v56, 0x3d2aaaab
	v_fmaak_f32 v56, v48, v56, 0x3e2aaaab
	v_fmamk_f32 v57, v53, 0x39500d01, v191
	v_fma_f32 v56, v48, v56, 0.5
	v_fmaak_f32 v57, v53, v57, 0x3c088889
	v_fma_f32 v56, v48, v56, 1.0
	v_fmaak_f32 v57, v53, v57, 0x3d2aaaab
	v_fmaak_f32 v57, v53, v57, 0x3e2aaaab
	v_mul_f32_e64 v48, v48, -v56
	v_fma_f32 v57, v53, v57, 0.5
	v_bfe_u32 v56, v48, 16, 1
	v_fma_f32 v57, v53, v57, 1.0
	v_add3_u32 v48, v48, v56, s71
	v_div_fixup_f32 v49, v52, v49, 1.0
	ds_read_u16 v52, v137 offset:4352
	ds_write_b16_d16_hi v121, v48 offset:17408
	v_mul_f32_e64 v48, v53, -v57
	v_max_f32_e32 v48, 0, v48
	v_sqrt_f32_e32 v48, v48
	s_waitcnt lgkmcnt(1)
	v_lshlrev_b32_e32 v52, 16, v52
	v_mul_f32_e32 v48, v49, v48
	v_mul_f32_e32 v48, v48, v52
	v_bfe_u32 v49, v48, 16, 1
	v_add3_u32 v48, v48, v49, s71
	ds_write_b16_d16_hi v121, v48 offset:33792
	v_add_f32_e32 v48, v54, v107
	v_mul_f32_e32 v48, 0xbfb8aa3b, v48
	v_exp_f32_e32 v48, v48
	s_nop 0
	v_add_f32_e32 v48, 1.0, v48
	v_div_scale_f32 v49, s[0:1], v48, v48, 1.0
	v_rcp_f32_e32 v52, v49
	s_nop 0
	v_fma_f32 v53, -v49, v52, 1.0
	v_fmac_f32_e32 v52, v53, v52
	v_div_scale_f32 v53, vcc, 1.0, v48, 1.0
	v_mul_f32_e32 v54, v53, v52
	v_fma_f32 v56, -v49, v54, v53
	v_fmac_f32_e32 v54, v56, v52
	v_fma_f32 v49, -v49, v54, v53
	v_div_fmas_f32 v49, v49, v52, v54
	v_div_fixup_f32 v48, v49, v48, 1.0
	v_add_f32_e32 v49, v50, v105
	v_mul_f32_e32 v49, 0xbfb8aa3b, v49
	v_exp_f32_e32 v49, v49
	v_mul_f32_e32 v48, v48, v154
	v_add_f32_e32 v49, 1.0, v49
	v_div_scale_f32 v50, s[0:1], v49, v49, 1.0
	v_rcp_f32_e32 v52, v50
	s_nop 0
	v_fma_f32 v53, -v50, v52, 1.0
	v_fmac_f32_e32 v52, v53, v52
	v_div_scale_f32 v53, vcc, 1.0, v49, 1.0
	v_mul_f32_e32 v54, v53, v52
	v_fma_f32 v56, -v50, v54, v53
	v_fmac_f32_e32 v54, v56, v52
	v_fma_f32 v50, -v50, v54, v53
	v_fmamk_f32 v53, v48, 0x3ab60b61, v181
	v_div_fmas_f32 v50, v50, v52, v54
	v_add_f32_e32 v52, v48, v48
	v_fmaak_f32 v53, v48, v53, 0x3d2aaaab
	v_fmaak_f32 v53, v48, v53, 0x3e2aaaab
	v_fmamk_f32 v54, v52, 0x39500d01, v191
	v_fma_f32 v53, v48, v53, 0.5
	v_fmaak_f32 v54, v52, v54, 0x3c088889
	v_fma_f32 v53, v48, v53, 1.0
	v_fmaak_f32 v54, v52, v54, 0x3d2aaaab
	v_fmaak_f32 v54, v52, v54, 0x3e2aaaab
	v_mul_f32_e64 v48, v48, -v53
	v_fma_f32 v54, v52, v54, 0.5
	v_bfe_u32 v53, v48, 16, 1
	v_fma_f32 v54, v52, v54, 1.0
	v_add3_u32 v48, v48, v53, s71
	v_div_fixup_f32 v49, v50, v49, 1.0
	ds_read_u16 v50, v137 offset:4624
	ds_write_b16_d16_hi v122, v48 offset:17408
	v_mul_f32_e64 v48, v52, -v54
	v_max_f32_e32 v48, 0, v48
	v_sqrt_f32_e32 v48, v48
	s_waitcnt lgkmcnt(1)
; DEV float bf2f(u16 h) { return __uint_as_float(((unsigned)h) << 16); }
; DEV float sigmoidf_(float x) { return 1.f / (1.f + __expf(-x)); }
; PHASE void lru_phase(const Params& p, int layer, const u16* __restrict__ GC, u16* __restrict__ OC, float* __restrict__ LA, ...
;     ...
;         for (int mi = 0; mi < 4; ++mi)
; #pragma unroll
;           for (int j = 0; j < 4; ++j) {
;             const int t = mi * 16 + fq * 4 + j;
;             const float rr = sigmoidf_(aR[mi][ni][j] + bba);
;             const float gg = sigmoidf_(aG[mi][ni][j] + bbx);
;             const float xv = bf2f(sX[t * 136 + col]);
;             const float la = -c8 * rr;
;             const float l2 = la + la;
;             const float e1 = la * (1.f + la * (0.5f + la * (0.16666667f + la * (0.041666668f + la * (0.0083333338f + la * 0.0013888889f)))));
;             const float e2 = l2 * (1.f + l2 * (0.5f + l2 * (0.16666667f + l2 * (0.041666668f + l2 * (0.0083333338f + l2 * (0.0013888889f + l2 * 0.0001984127f))))));
;             sR[t * 128 + col] = f2bf(-e1);
;             sG[t * 128 + col] = f2bf(__builtin_amdgcn_sqrtf(fmaxf(-e2, 0.f)) * gg * xv);
;           }
	v_lshlrev_b32_e32 v50, 16, v50
	v_mul_f32_e32 v48, v49, v48
	v_mul_f32_e32 v48, v48, v50
	v_bfe_u32 v49, v48, 16, 1
	v_add3_u32 v48, v48, v49, s71
	ds_write_b16_d16_hi v122, v48 offset:33792
	v_add_f32_e32 v48, v55, v107
	v_mul_f32_e32 v48, 0xbfb8aa3b, v48
	v_exp_f32_e32 v48, v48
	s_nop 0
	v_add_f32_e32 v48, 1.0, v48
	v_div_scale_f32 v49, s[0:1], v48, v48, 1.0
	v_rcp_f32_e32 v50, v49
	s_nop 0
	v_fma_f32 v52, -v49, v50, 1.0
	v_fmac_f32_e32 v50, v52, v50
	v_div_scale_f32 v52, vcc, 1.0, v48, 1.0
	v_mul_f32_e32 v53, v52, v50
	v_fma_f32 v54, -v49, v53, v52
	v_fmac_f32_e32 v53, v54, v50
	v_fma_f32 v49, -v49, v53, v52
	v_div_fmas_f32 v49, v49, v50, v53
	v_div_fixup_f32 v48, v49, v48, 1.0
	v_add_f32_e32 v49, v51, v105
	v_mul_f32_e32 v49, 0xbfb8aa3b, v49
	v_exp_f32_e32 v49, v49
	v_mul_f32_e32 v48, v48, v154
	v_add_f32_e32 v49, 1.0, v49
	v_div_scale_f32 v50, s[0:1], v49, v49, 1.0
	v_rcp_f32_e32 v51, v50
	s_nop 0
	v_fma_f32 v52, -v50, v51, 1.0
	v_fmac_f32_e32 v51, v52, v51
	v_div_scale_f32 v52, vcc, 1.0, v49, 1.0
	v_mul_f32_e32 v53, v52, v51
	v_fma_f32 v54, -v50, v53, v52
	v_fmac_f32_e32 v53, v54, v51
	v_fma_f32 v50, -v50, v53, v52
	v_fmamk_f32 v52, v48, 0x3ab60b61, v181
	v_div_fmas_f32 v50, v50, v51, v53
	v_add_f32_e32 v51, v48, v48
	v_fmaak_f32 v52, v48, v52, 0x3d2aaaab
	v_fmaak_f32 v52, v48, v52, 0x3e2aaaab
	v_fmamk_f32 v53, v51, 0x39500d01, v191
	v_fma_f32 v52, v48, v52, 0.5
	v_fmaak_f32 v53, v51, v53, 0x3c088889
	v_fma_f32 v52, v48, v52, 1.0
	v_fmaak_f32 v53, v51, v53, 0x3d2aaaab
	v_fmaak_f32 v53, v51, v53, 0x3e2aaaab
	v_mul_f32_e64 v48, v48, -v52
	v_fma_f32 v53, v51, v53, 0.5
	v_bfe_u32 v52, v48, 16, 1
	v_fma_f32 v53, v51, v53, 1.0
	v_add3_u32 v48, v48, v52, s71
	v_div_fixup_f32 v49, v50, v49, 1.0
	ds_read_u16 v50, v137 offset:4896
	ds_write_b16_d16_hi v123, v48 offset:17408
	v_mul_f32_e64 v48, v51, -v53
	v_max_f32_e32 v48, 0, v48
	v_sqrt_f32_e32 v48, v48
	s_waitcnt lgkmcnt(1)
	v_lshlrev_b32_e32 v50, 16, v50
	v_mul_f32_e32 v48, v49, v48
	v_mul_f32_e32 v48, v48, v50
	v_bfe_u32 v49, v48, 16, 1
	v_add3_u32 v48, v48, v49, s71
	ds_write_b16_d16_hi v123, v48 offset:33792
	v_div_scale_f32 v48, s[0:1], v44, v44, 1.0
	v_rcp_f32_e32 v49, v48
	s_nop 0
	v_fma_f32 v50, -v48, v49, 1.0
	v_fmac_f32_e32 v49, v50, v49
	v_div_scale_f32 v50, vcc, 1.0, v44, 1.0
	v_mul_f32_e32 v51, v50, v49
	v_fma_f32 v52, -v48, v51, v50
	v_fmac_f32_e32 v51, v52, v49
	v_fma_f32 v48, -v48, v51, v50
	v_div_fmas_f32 v48, v48, v49, v51
	v_div_fixup_f32 v44, v48, v44, 1.0
	v_div_scale_f32 v48, s[0:1], v40, v40, 1.0
	v_rcp_f32_e32 v49, v48
	v_mul_f32_e32 v44, v44, v154
	v_fma_f32 v50, -v48, v49, 1.0
	v_fmac_f32_e32 v49, v50, v49
	v_div_scale_f32 v50, vcc, 1.0, v40, 1.0
	v_mul_f32_e32 v51, v50, v49
	v_fma_f32 v52, -v48, v51, v50
	v_fmac_f32_e32 v51, v52, v49
	v_fma_f32 v48, -v48, v51, v50
	v_fmamk_f32 v50, v44, 0x3ab60b61, v181
	v_div_fmas_f32 v48, v48, v49, v51
	v_add_f32_e32 v49, v44, v44
	v_fmaak_f32 v50, v44, v50, 0x3d2aaaab
	v_fmaak_f32 v50, v44, v50, 0x3e2aaaab
	v_fmamk_f32 v51, v49, 0x39500d01, v191
	v_fma_f32 v50, v44, v50, 0.5
	v_fmaak_f32 v51, v49, v51, 0x3c088889
	v_fma_f32 v50, v44, v50, 1.0
	v_fmaak_f32 v51, v49, v51, 0x3d2aaaab
	v_fmaak_f32 v51, v49, v51, 0x3e2aaaab
	v_mul_f32_e64 v44, v44, -v50
	v_fma_f32 v51, v49, v51, 0.5
	v_bfe_u32 v50, v44, 16, 1
	v_fma_f32 v51, v49, v51, 1.0
	v_add3_u32 v44, v44, v50, s71
	v_div_fixup_f32 v40, v48, v40, 1.0
	ds_read_u16 v48, v137 offset:8432
	ds_write_b16_d16_hi v124, v44 offset:17408
	v_mul_f32_e64 v44, v49, -v51
	v_max_f32_e32 v44, 0, v44
	v_sqrt_f32_e32 v44, v44
	s_waitcnt lgkmcnt(1)
	v_lshlrev_b32_e32 v48, 16, v48
	v_mul_f32_e32 v40, v40, v44
	v_mul_f32_e32 v40, v40, v48
	v_bfe_u32 v44, v40, 16, 1
	v_add3_u32 v40, v40, v44, s71
	ds_write_b16_d16_hi v124, v40 offset:33792
	v_add_f32_e32 v40, v45, v107
	v_mul_f32_e32 v40, 0xbfb8aa3b, v40
	v_exp_f32_e32 v40, v40
	s_nop 0
	v_add_f32_e32 v40, 1.0, v40
	v_div_scale_f32 v44, s[0:1], v40, v40, 1.0
	v_rcp_f32_e32 v45, v44
	s_nop 0
	v_fma_f32 v48, -v44, v45, 1.0
	v_fmac_f32_e32 v45, v48, v45
	v_div_scale_f32 v48, vcc, 1.0, v40, 1.0
	v_mul_f32_e32 v49, v48, v45
	v_fma_f32 v50, -v44, v49, v48
	v_fmac_f32_e32 v49, v50, v45
	v_fma_f32 v44, -v44, v49, v48
	v_div_fmas_f32 v44, v44, v45, v49
	v_div_fixup_f32 v40, v44, v40, 1.0
	v_div_scale_f32 v44, s[0:1], v41, v41, 1.0
	v_rcp_f32_e32 v45, v44
	v_mul_f32_e32 v40, v40, v154
	v_fma_f32 v48, -v44, v45, 1.0
	v_fmac_f32_e32 v45, v48, v45
	v_div_scale_f32 v48, vcc, 1.0, v41, 1.0
	v_mul_f32_e32 v49, v48, v45
	v_fma_f32 v50, -v44, v49, v48
	v_fmac_f32_e32 v49, v50, v45
	v_fma_f32 v44, -v44, v49, v48
	v_fmamk_f32 v48, v40, 0x3ab60b61, v181
	v_div_fmas_f32 v44, v44, v45, v49
	v_add_f32_e32 v45, v40, v40
	v_fmaak_f32 v48, v40, v48, 0x3d2aaaab
	v_fmaak_f32 v48, v40, v48, 0x3e2aaaab
	v_fmamk_f32 v49, v45, 0x39500d01, v191
	v_fma_f32 v48, v40, v48, 0.5
	v_fmaak_f32 v49, v45, v49, 0x3c088889
	v_fma_f32 v48, v40, v48, 1.0
	v_fmaak_f32 v49, v45, v49, 0x3d2aaaab
	v_fmaak_f32 v49, v45, v49, 0x3e2aaaab
	v_mul_f32_e64 v40, v40, -v48
	v_fma_f32 v49, v45, v49, 0.5
	v_bfe_u32 v48, v40, 16, 1
	v_fma_f32 v49, v45, v49, 1.0
	v_add3_u32 v40, v40, v48, s71
	v_div_fixup_f32 v41, v44, v41, 1.0
	ds_read_u16 v44, v137 offset:8704
	ds_write_b16_d16_hi v125, v40 offset:17408
	v_mul_f32_e64 v40, v45, -v49
	v_max_f32_e32 v40, 0, v40
	v_sqrt_f32_e32 v40, v40
	s_waitcnt lgkmcnt(1)
; DEV float bf2f(u16 h) { return __uint_as_float(((unsigned)h) << 16); }
; DEV float sigmoidf_(float x) { return 1.f / (1.f + __expf(-x)); }
; PHASE void lru_phase(const Params& p, int layer, const u16* __restrict__ GC, u16* __restrict__ OC, float* __restrict__ LA, ...
;     ...
;         for (int mi = 0; mi < 4; ++mi)
; #pragma unroll
;           for (int j = 0; j < 4; ++j) {
;             const int t = mi * 16 + fq * 4 + j;
;             const float rr = sigmoidf_(aR[mi][ni][j] + bba);
;             const float gg = sigmoidf_(aG[mi][ni][j] + bbx);
;             const float xv = bf2f(sX[t * 136 + col]);
;             const float la = -c8 * rr;
;             const float l2 = la + la;
;             const float e1 = la * (1.f + la * (0.5f + la * (0.16666667f + la * (0.041666668f + la * (0.0083333338f + la * 0.0013888889f)))));
;             const float e2 = l2 * (1.f + l2 * (0.5f + l2 * (0.16666667f + l2 * (0.041666668f + l2 * (0.0083333338f + l2 * (0.0013888889f + l2 * 0.0001984127f))))));
;             sR[t * 128 + col] = f2bf(-e1);
;             sG[t * 128 + col] = f2bf(__builtin_amdgcn_sqrtf(fmaxf(-e2, 0.f)) * gg * xv);
;           }
	v_lshlrev_b32_e32 v44, 16, v44
	v_mul_f32_e32 v40, v41, v40
	v_mul_f32_e32 v40, v40, v44
	v_bfe_u32 v41, v40, 16, 1
	v_add3_u32 v40, v40, v41, s71
	ds_write_b16_d16_hi v125, v40 offset:33792
	v_add_f32_e32 v40, v46, v107
	v_mul_f32_e32 v40, 0xbfb8aa3b, v40
	v_exp_f32_e32 v40, v40
	s_nop 0
	v_add_f32_e32 v40, 1.0, v40
	v_div_scale_f32 v41, s[0:1], v40, v40, 1.0
	v_rcp_f32_e32 v44, v41
	s_nop 0
	v_fma_f32 v45, -v41, v44, 1.0
	v_fmac_f32_e32 v44, v45, v44
	v_div_scale_f32 v45, vcc, 1.0, v40, 1.0
	v_mul_f32_e32 v46, v45, v44
	v_fma_f32 v48, -v41, v46, v45
	v_fmac_f32_e32 v46, v48, v44
	v_fma_f32 v41, -v41, v46, v45
	v_div_fmas_f32 v41, v41, v44, v46
	v_div_fixup_f32 v40, v41, v40, 1.0
	v_add_f32_e32 v41, v42, v105
	v_mul_f32_e32 v41, 0xbfb8aa3b, v41
	v_exp_f32_e32 v41, v41
	v_mul_f32_e32 v40, v40, v154
	v_add_f32_e32 v41, 1.0, v41
	v_div_scale_f32 v42, s[0:1], v41, v41, 1.0
	v_rcp_f32_e32 v44, v42
	s_nop 0
	v_fma_f32 v45, -v42, v44, 1.0
	v_fmac_f32_e32 v44, v45, v44
	v_div_scale_f32 v45, vcc, 1.0, v41, 1.0
	v_mul_f32_e32 v46, v45, v44
	v_fma_f32 v48, -v42, v46, v45
	v_fmac_f32_e32 v46, v48, v44
	v_fma_f32 v42, -v42, v46, v45
	v_fmamk_f32 v45, v40, 0x3ab60b61, v181
	v_div_fmas_f32 v42, v42, v44, v46
	v_add_f32_e32 v44, v40, v40
	v_fmaak_f32 v45, v40, v45, 0x3d2aaaab
	v_fmaak_f32 v45, v40, v45, 0x3e2aaaab
	v_fmamk_f32 v46, v44, 0x39500d01, v191
	v_fma_f32 v45, v40, v45, 0.5
	v_fmaak_f32 v46, v44, v46, 0x3c088889
	v_fma_f32 v45, v40, v45, 1.0
	v_fmaak_f32 v46, v44, v46, 0x3d2aaaab
	v_fmaak_f32 v46, v44, v46, 0x3e2aaaab
	v_mul_f32_e64 v40, v40, -v45
	v_fma_f32 v46, v44, v46, 0.5
	v_bfe_u32 v45, v40, 16, 1
	v_fma_f32 v46, v44, v46, 1.0
	v_add3_u32 v40, v40, v45, s71
	v_div_fixup_f32 v41, v42, v41, 1.0
	ds_read_u16 v42, v137 offset:8976
	ds_write_b16_d16_hi v126, v40 offset:17408
	v_mul_f32_e64 v40, v44, -v46
	v_max_f32_e32 v40, 0, v40
	v_sqrt_f32_e32 v40, v40
	s_waitcnt lgkmcnt(1)
	v_lshlrev_b32_e32 v42, 16, v42
	v_mul_f32_e32 v40, v41, v40
	v_mul_f32_e32 v40, v40, v42
	v_bfe_u32 v41, v40, 16, 1
	v_add3_u32 v40, v40, v41, s71
	ds_write_b16_d16_hi v126, v40 offset:33792
	v_add_f32_e32 v40, v47, v107
	v_mul_f32_e32 v40, 0xbfb8aa3b, v40
	v_exp_f32_e32 v40, v40
	s_nop 0
	v_add_f32_e32 v40, 1.0, v40
	v_div_scale_f32 v41, s[0:1], v40, v40, 1.0
	v_rcp_f32_e32 v42, v41
	s_nop 0
	v_fma_f32 v44, -v41, v42, 1.0
	v_fmac_f32_e32 v42, v44, v42
	v_div_scale_f32 v44, vcc, 1.0, v40, 1.0
	v_mul_f32_e32 v45, v44, v42
	v_fma_f32 v46, -v41, v45, v44
	v_fmac_f32_e32 v45, v46, v42
	v_fma_f32 v41, -v41, v45, v44
	v_div_fmas_f32 v41, v41, v42, v45
	v_div_fixup_f32 v40, v41, v40, 1.0
	v_add_f32_e32 v41, v43, v105
	v_mul_f32_e32 v41, 0xbfb8aa3b, v41
	v_exp_f32_e32 v41, v41
	v_mul_f32_e32 v40, v40, v154
	v_add_f32_e32 v41, 1.0, v41
	v_div_scale_f32 v42, s[0:1], v41, v41, 1.0
	v_rcp_f32_e32 v43, v42
	s_nop 0
	v_fma_f32 v44, -v42, v43, 1.0
	v_fmac_f32_e32 v43, v44, v43
	v_div_scale_f32 v44, vcc, 1.0, v41, 1.0
	v_mul_f32_e32 v45, v44, v43
	v_fma_f32 v46, -v42, v45, v44
	v_fmac_f32_e32 v45, v46, v43
	v_fma_f32 v42, -v42, v45, v44
	v_fmamk_f32 v44, v40, 0x3ab60b61, v181
	v_div_fmas_f32 v42, v42, v43, v45
	v_add_f32_e32 v43, v40, v40
	v_fmaak_f32 v44, v40, v44, 0x3d2aaaab
	v_fmaak_f32 v44, v40, v44, 0x3e2aaaab
	v_fmamk_f32 v45, v43, 0x39500d01, v191
	v_fma_f32 v44, v40, v44, 0.5
	v_fmaak_f32 v45, v43, v45, 0x3c088889
	v_fma_f32 v44, v40, v44, 1.0
	v_fmaak_f32 v45, v43, v45, 0x3d2aaaab
	v_fmaak_f32 v45, v43, v45, 0x3e2aaaab
	v_mul_f32_e64 v40, v40, -v44
	v_fma_f32 v45, v43, v45, 0.5
	v_bfe_u32 v44, v40, 16, 1
	v_fma_f32 v45, v43, v45, 1.0
	v_add3_u32 v40, v40, v44, s71
	v_div_fixup_f32 v41, v42, v41, 1.0
	ds_read_u16 v42, v137 offset:9248
	ds_write_b16_d16_hi v127, v40 offset:17408
	v_mul_f32_e64 v40, v43, -v45
	v_max_f32_e32 v40, 0, v40
	v_sqrt_f32_e32 v40, v40
	s_waitcnt lgkmcnt(1)
	v_lshlrev_b32_e32 v42, 16, v42
	v_mul_f32_e32 v40, v41, v40
	v_mul_f32_e32 v40, v40, v42
	v_bfe_u32 v41, v40, 16, 1
	v_add3_u32 v40, v40, v41, s71
	ds_write_b16_d16_hi v127, v40 offset:33792
	v_div_scale_f32 v40, s[0:1], v36, v36, 1.0
	v_rcp_f32_e32 v41, v40
	s_nop 0
	v_fma_f32 v42, -v40, v41, 1.0
	v_fmac_f32_e32 v41, v42, v41
	v_div_scale_f32 v42, vcc, 1.0, v36, 1.0
	v_mul_f32_e32 v43, v42, v41
	v_fma_f32 v44, -v40, v43, v42
	v_fmac_f32_e32 v43, v44, v41
	v_fma_f32 v40, -v40, v43, v42
	v_div_fmas_f32 v40, v40, v41, v43
	v_div_fixup_f32 v36, v40, v36, 1.0
	v_div_scale_f32 v40, s[0:1], v32, v32, 1.0
	v_rcp_f32_e32 v41, v40
	v_mul_f32_e32 v36, v36, v154
	v_fma_f32 v42, -v40, v41, 1.0
	v_fmac_f32_e32 v41, v42, v41
	v_div_scale_f32 v42, vcc, 1.0, v32, 1.0
	v_mul_f32_e32 v43, v42, v41
	v_fma_f32 v44, -v40, v43, v42
	v_fmac_f32_e32 v43, v44, v41
	v_fma_f32 v40, -v40, v43, v42
	v_fmamk_f32 v42, v36, 0x3ab60b61, v181
	v_div_fmas_f32 v40, v40, v41, v43
	v_add_f32_e32 v41, v36, v36
	v_fmaak_f32 v42, v36, v42, 0x3d2aaaab
	v_fmaak_f32 v42, v36, v42, 0x3e2aaaab
	v_fmamk_f32 v43, v41, 0x39500d01, v191
	v_fma_f32 v42, v36, v42, 0.5
	v_fmaak_f32 v43, v41, v43, 0x3c088889
	v_fma_f32 v42, v36, v42, 1.0
	v_fmaak_f32 v43, v41, v43, 0x3d2aaaab
	v_fmaak_f32 v43, v41, v43, 0x3e2aaaab
	v_mul_f32_e64 v36, v36, -v42
	v_fma_f32 v43, v41, v43, 0.5
	v_bfe_u32 v42, v36, 16, 1
	v_fma_f32 v43, v41, v43, 1.0
	v_add3_u32 v36, v36, v42, s71
	v_div_fixup_f32 v32, v40, v32, 1.0
	ds_read_u16 v40, v137 offset:12784
	ds_write_b16_d16_hi v128, v36 offset:17408
	v_mul_f32_e64 v36, v41, -v43
	v_max_f32_e32 v36, 0, v36
	v_sqrt_f32_e32 v36, v36
	s_waitcnt lgkmcnt(1)
; DEV float bf2f(u16 h) { return __uint_as_float(((unsigned)h) << 16); }
; DEV float sigmoidf_(float x) { return 1.f / (1.f + __expf(-x)); }
; PHASE void lru_phase(const Params& p, int layer, const u16* __restrict__ GC, u16* __restrict__ OC, float* __restrict__ LA, ...
;     ...
;         for (int mi = 0; mi < 4; ++mi)
; #pragma unroll
;           for (int j = 0; j < 4; ++j) {
;             const int t = mi * 16 + fq * 4 + j;
;             const float rr = sigmoidf_(aR[mi][ni][j] + bba);
;             const float gg = sigmoidf_(aG[mi][ni][j] + bbx);
;             const float xv = bf2f(sX[t * 136 + col]);
;             const float la = -c8 * rr;
;             const float l2 = la + la;
;             const float e1 = la * (1.f + la * (0.5f + la * (0.16666667f + la * (0.041666668f + la * (0.0083333338f + la * 0.0013888889f)))));
;             const float e2 = l2 * (1.f + l2 * (0.5f + l2 * (0.16666667f + l2 * (0.041666668f + l2 * (0.0083333338f + l2 * (0.0013888889f + l2 * 0.0001984127f))))));
;             sR[t * 128 + col] = f2bf(-e1);
;             sG[t * 128 + col] = f2bf(__builtin_amdgcn_sqrtf(fmaxf(-e2, 0.f)) * gg * xv);
;           }
	v_lshlrev_b32_e32 v40, 16, v40
	v_mul_f32_e32 v32, v32, v36
	v_mul_f32_e32 v32, v32, v40
	v_bfe_u32 v36, v32, 16, 1
	v_add3_u32 v32, v32, v36, s71
	ds_write_b16_d16_hi v128, v32 offset:33792
	v_add_f32_e32 v32, v37, v107
	v_mul_f32_e32 v32, 0xbfb8aa3b, v32
	v_exp_f32_e32 v32, v32
	s_nop 0
	v_add_f32_e32 v32, 1.0, v32
	v_div_scale_f32 v36, s[0:1], v32, v32, 1.0
	v_rcp_f32_e32 v37, v36
	s_nop 0
	v_fma_f32 v40, -v36, v37, 1.0
	v_fmac_f32_e32 v37, v40, v37
	v_div_scale_f32 v40, vcc, 1.0, v32, 1.0
	v_mul_f32_e32 v41, v40, v37
	v_fma_f32 v42, -v36, v41, v40
	v_fmac_f32_e32 v41, v42, v37
	v_fma_f32 v36, -v36, v41, v40
	v_div_fmas_f32 v36, v36, v37, v41
	v_div_fixup_f32 v32, v36, v32, 1.0
	v_div_scale_f32 v36, s[0:1], v33, v33, 1.0
	v_rcp_f32_e32 v37, v36
	v_mul_f32_e32 v32, v32, v154
	v_fma_f32 v40, -v36, v37, 1.0
	v_fmac_f32_e32 v37, v40, v37
	v_div_scale_f32 v40, vcc, 1.0, v33, 1.0
	v_mul_f32_e32 v41, v40, v37
	v_fma_f32 v42, -v36, v41, v40
	v_fmac_f32_e32 v41, v42, v37
	v_fma_f32 v36, -v36, v41, v40
	v_fmamk_f32 v40, v32, 0x3ab60b61, v181
	v_div_fmas_f32 v36, v36, v37, v41
	v_add_f32_e32 v37, v32, v32
	v_fmaak_f32 v40, v32, v40, 0x3d2aaaab
	v_fmaak_f32 v40, v32, v40, 0x3e2aaaab
	v_fmamk_f32 v41, v37, 0x39500d01, v191
	v_fma_f32 v40, v32, v40, 0.5
	v_fmaak_f32 v41, v37, v41, 0x3c088889
	v_fma_f32 v40, v32, v40, 1.0
	v_fmaak_f32 v41, v37, v41, 0x3d2aaaab
	v_fmaak_f32 v41, v37, v41, 0x3e2aaaab
	v_mul_f32_e64 v32, v32, -v40
	v_fma_f32 v41, v37, v41, 0.5
	v_bfe_u32 v40, v32, 16, 1
	v_fma_f32 v41, v37, v41, 1.0
	v_add3_u32 v32, v32, v40, s71
	v_div_fixup_f32 v33, v36, v33, 1.0
	ds_read_u16 v36, v137 offset:13056
	ds_write_b16_d16_hi v129, v32 offset:17408
	v_mul_f32_e64 v32, v37, -v41
	v_max_f32_e32 v32, 0, v32
	v_sqrt_f32_e32 v32, v32
	s_waitcnt lgkmcnt(1)
	v_lshlrev_b32_e32 v36, 16, v36
	v_mul_f32_e32 v32, v33, v32
	v_mul_f32_e32 v32, v32, v36
	v_bfe_u32 v33, v32, 16, 1
	v_add3_u32 v32, v32, v33, s71
	ds_write_b16_d16_hi v129, v32 offset:33792
	v_add_f32_e32 v32, v38, v107
	v_mul_f32_e32 v32, 0xbfb8aa3b, v32
	v_exp_f32_e32 v32, v32
	s_nop 0
	v_add_f32_e32 v32, 1.0, v32
	v_div_scale_f32 v33, s[0:1], v32, v32, 1.0
	v_rcp_f32_e32 v36, v33
	s_nop 0
	v_fma_f32 v37, -v33, v36, 1.0
	v_fmac_f32_e32 v36, v37, v36
	v_div_scale_f32 v37, vcc, 1.0, v32, 1.0
	v_mul_f32_e32 v38, v37, v36
	v_fma_f32 v40, -v33, v38, v37
	v_fmac_f32_e32 v38, v40, v36
	v_fma_f32 v33, -v33, v38, v37
	v_div_fmas_f32 v33, v33, v36, v38
	v_div_fixup_f32 v32, v33, v32, 1.0
	v_add_f32_e32 v33, v34, v105
	v_mul_f32_e32 v33, 0xbfb8aa3b, v33
	v_exp_f32_e32 v33, v33
	v_mul_f32_e32 v32, v32, v154
	v_add_f32_e32 v33, 1.0, v33
	v_div_scale_f32 v34, s[0:1], v33, v33, 1.0
	v_rcp_f32_e32 v36, v34
	s_nop 0
	v_fma_f32 v37, -v34, v36, 1.0
	v_fmac_f32_e32 v36, v37, v36
	v_div_scale_f32 v37, vcc, 1.0, v33, 1.0
	v_mul_f32_e32 v38, v37, v36
	v_fma_f32 v40, -v34, v38, v37
	v_fmac_f32_e32 v38, v40, v36
	v_fma_f32 v34, -v34, v38, v37
	v_fmamk_f32 v37, v32, 0x3ab60b61, v181
	v_div_fmas_f32 v34, v34, v36, v38
	v_add_f32_e32 v36, v32, v32
	v_fmaak_f32 v37, v32, v37, 0x3d2aaaab
	v_fmaak_f32 v37, v32, v37, 0x3e2aaaab
	v_fmamk_f32 v38, v36, 0x39500d01, v191
	v_fma_f32 v37, v32, v37, 0.5
	v_fmaak_f32 v38, v36, v38, 0x3c088889
	v_fma_f32 v37, v32, v37, 1.0
	v_fmaak_f32 v38, v36, v38, 0x3d2aaaab
	v_fmaak_f32 v38, v36, v38, 0x3e2aaaab
	v_mul_f32_e64 v32, v32, -v37
	v_fma_f32 v38, v36, v38, 0.5
	v_bfe_u32 v37, v32, 16, 1
	v_fma_f32 v38, v36, v38, 1.0
	v_add3_u32 v32, v32, v37, s71
	v_div_fixup_f32 v33, v34, v33, 1.0
	ds_read_u16 v34, v137 offset:13328
	ds_write_b16_d16_hi v130, v32 offset:17408
	v_mul_f32_e64 v32, v36, -v38
	v_max_f32_e32 v32, 0, v32
	v_sqrt_f32_e32 v32, v32
	s_waitcnt lgkmcnt(1)
	v_lshlrev_b32_e32 v34, 16, v34
	v_mul_f32_e32 v32, v33, v32
	v_mul_f32_e32 v32, v32, v34
	v_bfe_u32 v33, v32, 16, 1
	v_add3_u32 v32, v32, v33, s71
	ds_write_b16_d16_hi v130, v32 offset:33792
	v_add_f32_e32 v32, v39, v107
	v_mul_f32_e32 v32, 0xbfb8aa3b, v32
	v_exp_f32_e32 v32, v32
	s_nop 0
	v_add_f32_e32 v32, 1.0, v32
	v_div_scale_f32 v33, s[0:1], v32, v32, 1.0
	v_rcp_f32_e32 v34, v33
	s_nop 0
	v_fma_f32 v36, -v33, v34, 1.0
	v_fmac_f32_e32 v34, v36, v34
	v_div_scale_f32 v36, vcc, 1.0, v32, 1.0
	v_mul_f32_e32 v37, v36, v34
	v_fma_f32 v38, -v33, v37, v36
	v_fmac_f32_e32 v37, v38, v34
	v_fma_f32 v33, -v33, v37, v36
	v_div_fmas_f32 v33, v33, v34, v37
	v_div_fixup_f32 v32, v33, v32, 1.0
	v_add_f32_e32 v33, v35, v105
	v_mul_f32_e32 v33, 0xbfb8aa3b, v33
	v_exp_f32_e32 v33, v33
	v_mul_f32_e32 v32, v32, v154
	v_add_f32_e32 v33, 1.0, v33
	v_div_scale_f32 v34, s[0:1], v33, v33, 1.0
	v_rcp_f32_e32 v35, v34
	s_nop 0
	v_fma_f32 v36, -v34, v35, 1.0
	v_fmac_f32_e32 v35, v36, v35
	v_div_scale_f32 v36, vcc, 1.0, v33, 1.0
	v_mul_f32_e32 v37, v36, v35
	v_fma_f32 v38, -v34, v37, v36
	v_fmac_f32_e32 v37, v38, v35
	v_fma_f32 v34, -v34, v37, v36
	v_fmamk_f32 v36, v32, 0x3ab60b61, v181
	v_div_fmas_f32 v34, v34, v35, v37
	v_add_f32_e32 v35, v32, v32
	v_fmaak_f32 v36, v32, v36, 0x3d2aaaab
	v_fmaak_f32 v36, v32, v36, 0x3e2aaaab
	v_fmamk_f32 v37, v35, 0x39500d01, v191
	v_fma_f32 v36, v32, v36, 0.5
	v_fmaak_f32 v37, v35, v37, 0x3c088889
	v_fma_f32 v36, v32, v36, 1.0
	v_fmaak_f32 v37, v35, v37, 0x3d2aaaab
	v_fmaak_f32 v37, v35, v37, 0x3e2aaaab
	v_mul_f32_e64 v32, v32, -v36
	v_fma_f32 v37, v35, v37, 0.5
	v_bfe_u32 v36, v32, 16, 1
	v_fma_f32 v37, v35, v37, 1.0
	v_add3_u32 v32, v32, v36, s71
	v_div_fixup_f32 v33, v34, v33, 1.0
	ds_read_u16 v34, v137 offset:13600
	ds_write_b16_d16_hi v131, v32 offset:17408
	v_mul_f32_e64 v32, v35, -v37
	v_max_f32_e32 v32, 0, v32
	v_sqrt_f32_e32 v32, v32
	s_waitcnt lgkmcnt(1)
; DEV float bf2f(u16 h) { return __uint_as_float(((unsigned)h) << 16); }
; DEV float sigmoidf_(float x) { return 1.f / (1.f + __expf(-x)); }
; PHASE void lru_phase(const Params& p, int layer, const u16* __restrict__ GC, u16* __restrict__ OC, float* __restrict__ LA, ...
;     ...
;       for (int ni = 0; ni < 2; ++ni) {
;         const int col = wid * 32 + ni * 16 + fr;
;         const float bba = ba[ch0 + col], bbx = bx[ch0 + col];
;         const float c8 = 8.f * log1pf(expf(-lam[ch0 + col]));
; #pragma unroll
;         for (int mi = 0; mi < 4; ++mi)
; #pragma unroll
;           for (int j = 0; j < 4; ++j) {
;             const int t = mi * 16 + fq * 4 + j;
;             const float rr = sigmoidf_(aR[mi][ni][j] + bba);
;             const float gg = sigmoidf_(aG[mi][ni][j] + bbx);
;             const float xv = bf2f(sX[t * 136 + col]);
;             const float la = -c8 * rr;
;             const float l2 = la + la;
;             const float e1 = la * (1.f + la * (0.5f + la * (0.16666667f + la * (0.041666668f + la * (0.0083333338f + la * 0.0013888889f)))));
;             const float e2 = l2 * (1.f + l2 * (0.5f + l2 * (0.16666667f + l2 * (0.041666668f + l2 * (0.0083333338f + l2 * (0.0013888889f + l2 * 0.0001984127f))))));
;             sR[t * 128 + col] = f2bf(-e1);
;             sG[t * 128 + col] = f2bf(__builtin_amdgcn_sqrtf(fmaxf(-e2, 0.f)) * gg * xv);
;           }
	v_lshlrev_b32_e32 v34, 16, v34
	v_mul_f32_e32 v32, v33, v32
	v_mul_f32_e32 v32, v32, v34
	v_bfe_u32 v33, v32, 16, 1
	v_add3_u32 v32, v32, v33, s71
	ds_write_b16_d16_hi v131, v32 offset:33792
	global_load_dword v33, v[110:111], off offset:64
	global_load_dword v32, v[112:113], off offset:64
	global_load_dword v34, v[108:109], off offset:64
	s_waitcnt vmcnt(2)
	v_add_f32_e32 v28, v28, v33
	v_mul_f32_e32 v28, 0xbfb8aa3b, v28
	s_waitcnt vmcnt(0)
	v_mul_f32_e32 v35, 0xbfb8aa3b, v34
	v_fma_f32 v36, v34, s25, -v35
	v_rndne_f32_e32 v37, v35
	v_fmac_f32_e32 v36, 0xb2a5705f, v34
	v_sub_f32_e32 v35, v35, v37
	v_add_f32_e32 v35, v35, v36
	v_exp_f32_e32 v35, v35
	v_cvt_i32_f32_e32 v36, v37
	v_cmp_nlt_f32_e32 vcc, s26, v34
	v_exp_f32_e32 v28, v28
	v_add_f32_e32 v24, v24, v32
	v_ldexp_f32 v35, v35, v36
	v_cndmask_b32_e32 v35, 0, v35, vcc
	v_cmp_ngt_f32_e32 vcc, s27, v34
	v_add_f32_e32 v28, 1.0, v28
	v_mul_f32_e32 v24, 0xbfb8aa3b, v24
	v_cndmask_b32_e32 v36, v167, v35, vcc
	v_add_f32_e32 v37, 1.0, v36
	v_add_f32_e32 v34, -1.0, v37
	v_sub_f32_e32 v35, v34, v37
	v_add_f32_e32 v35, 1.0, v35
	v_sub_f32_e32 v34, v36, v34
	v_add_f32_e32 v38, v34, v35
	v_frexp_mant_f32_e32 v34, v37
	v_cmp_gt_f32_e32 vcc, s35, v34
	v_cvt_f64_f32_e32 v[34:35], v37
	v_frexp_exp_i32_f64_e32 v34, v[34:35]
	v_subbrev_co_u32_e32 v34, vcc, 0, v34, vcc
	v_sub_u32_e32 v35, 0, v34
	v_ldexp_f32 v37, v37, v35
	v_ldexp_f32 v35, v38, v35
	v_add_f32_e32 v38, -1.0, v37
	v_add_f32_e32 v39, 1.0, v38
	v_sub_f32_e32 v39, v37, v39
	v_add_f32_e32 v39, v35, v39
	v_add_f32_e32 v40, v38, v39
	v_sub_f32_e32 v38, v38, v40
	v_add_f32_e32 v38, v39, v38
	v_add_f32_e32 v39, 1.0, v37
	v_add_f32_e32 v41, -1.0, v39
	v_sub_f32_e32 v37, v37, v41
	v_add_f32_e32 v35, v35, v37
	v_add_f32_e32 v37, v39, v35
	v_sub_f32_e32 v39, v39, v37
	v_add_f32_e32 v35, v35, v39
	v_rcp_f32_e32 v39, v37
	v_cvt_f32_i32_e32 v34, v34
	v_cmp_neq_f32_e32 vcc, s24, v36
	v_exp_f32_e32 v24, v24
	v_mul_f32_e32 v41, v40, v39
	v_mul_f32_e32 v42, v37, v41
	v_fma_f32 v43, v41, v37, -v42
	v_fmac_f32_e32 v43, v41, v35
	v_add_f32_e32 v44, v42, v43
	v_sub_f32_e32 v45, v40, v44
	v_sub_f32_e32 v40, v40, v45
	v_sub_f32_e32 v42, v44, v42
	v_sub_f32_e32 v40, v40, v44
	v_add_f32_e32 v38, v38, v40
	v_sub_f32_e32 v40, v42, v43
	v_add_f32_e32 v38, v40, v38
	v_add_f32_e32 v40, v45, v38
	v_mul_f32_e32 v42, v39, v40
	v_mul_f32_e32 v43, v37, v42
	v_fma_f32 v37, v42, v37, -v43
	v_fmac_f32_e32 v37, v42, v35
	v_sub_f32_e32 v35, v45, v40
	v_add_f32_e32 v35, v38, v35
	v_add_f32_e32 v38, v43, v37
	v_sub_f32_e32 v44, v40, v38
	v_sub_f32_e32 v40, v40, v44
	v_sub_f32_e32 v43, v38, v43
	v_sub_f32_e32 v38, v40, v38
	v_add_f32_e32 v35, v35, v38
	v_sub_f32_e32 v37, v43, v37
	v_add_f32_e32 v35, v37, v35
	v_add_f32_e32 v37, v41, v42
	v_add_f32_e32 v35, v44, v35
	v_sub_f32_e32 v38, v37, v41
	v_mul_f32_e32 v35, v39, v35
	v_sub_f32_e32 v38, v42, v38
	v_add_f32_e32 v35, v38, v35
	v_mul_f32_e32 v41, 0x3f317218, v34
	v_add_f32_e32 v38, v37, v35
	v_fma_f32 v42, v34, s36, -v41
	v_mul_f32_e32 v39, v38, v38
	v_fmac_f32_e32 v42, 0xb102e308, v34
	v_sub_f32_e32 v34, v38, v37
	v_fmamk_f32 v40, v39, 0x3e9b6dac, v164
	v_sub_f32_e32 v34, v35, v34
	v_add_f32_e32 v35, v41, v42
	v_fmaak_f32 v40, v39, v40, 0x3f2aaada
	v_sub_f32_e32 v37, v35, v41
	v_ldexp_f32 v41, v38, 1
	v_mul_f32_e32 v38, v38, v39
	v_mul_f32_e32 v38, v38, v40
	v_add_f32_e32 v39, v41, v38
	v_sub_f32_e32 v40, v39, v41
	v_ldexp_f32 v34, v34, 1
	v_sub_f32_e32 v38, v38, v40
	v_add_f32_e32 v34, v34, v38
	v_add_f32_e32 v38, v39, v34
	v_sub_f32_e32 v39, v38, v39
	v_sub_f32_e32 v34, v34, v39
	v_add_f32_e32 v39, v35, v38
	v_sub_f32_e32 v40, v39, v35
	v_sub_f32_e32 v41, v39, v40
	v_sub_f32_e32 v37, v42, v37
	v_sub_f32_e32 v35, v35, v41
	v_sub_f32_e32 v38, v38, v40
	v_add_f32_e32 v35, v38, v35
	v_add_f32_e32 v38, v37, v34
	v_sub_f32_e32 v40, v38, v37
	v_sub_f32_e32 v41, v38, v40
	v_sub_f32_e32 v37, v37, v41
	v_sub_f32_e32 v34, v34, v40
	v_add_f32_e32 v35, v38, v35
	v_add_f32_e32 v34, v34, v37
	v_add_f32_e32 v37, v39, v35
	v_sub_f32_e32 v38, v37, v39
	v_sub_f32_e32 v35, v35, v38
	v_add_f32_e32 v34, v34, v35
	v_add_f32_e32 v34, v37, v34
	v_cndmask_b32_e32 v34, v167, v34, vcc
	v_cmp_lt_f32_e64 vcc, |v36|, s37
	v_div_scale_f32 v35, s[0:1], v28, v28, 1.0
	s_nop 0
	v_cndmask_b32_e32 v34, v34, v36, vcc
	v_rcp_f32_e32 v36, v35
	v_add_f32_e32 v24, 1.0, v24
	v_mul_f32_e32 v34, 0xc1000000, v34
	v_add_f32_e32 v25, v25, v32
	v_fma_f32 v37, -v35, v36, 1.0
	v_fmac_f32_e32 v36, v37, v36
	v_div_scale_f32 v37, vcc, 1.0, v28, 1.0
	v_mul_f32_e32 v38, v37, v36
	v_fma_f32 v39, -v35, v38, v37
	v_fmac_f32_e32 v38, v39, v36
	v_fma_f32 v35, -v35, v38, v37
	v_div_fmas_f32 v35, v35, v36, v38
	v_div_fixup_f32 v28, v35, v28, 1.0
	v_div_scale_f32 v35, s[0:1], v24, v24, 1.0
	v_rcp_f32_e32 v36, v35
	v_mul_f32_e32 v28, v28, v34
	v_mul_f32_e32 v25, 0xbfb8aa3b, v25
	v_exp_f32_e32 v25, v25
	v_fma_f32 v37, -v35, v36, 1.0
	v_fmac_f32_e32 v36, v37, v36
	v_div_scale_f32 v37, vcc, 1.0, v24, 1.0
	v_mul_f32_e32 v38, v37, v36
	v_fma_f32 v39, -v35, v38, v37
	v_fmac_f32_e32 v38, v39, v36
	v_fma_f32 v35, -v35, v38, v37
	v_fmamk_f32 v37, v28, 0x3ab60b61, v181
	v_div_fmas_f32 v35, v35, v36, v38
	v_add_f32_e32 v36, v28, v28
	v_fmaak_f32 v37, v28, v37, 0x3d2aaaab
	v_fmaak_f32 v37, v28, v37, 0x3e2aaaab
	v_fmamk_f32 v38, v36, 0x39500d01, v191
	v_fma_f32 v37, v28, v37, 0.5
	v_fmaak_f32 v38, v36, v38, 0x3c088889
	v_fma_f32 v37, v28, v37, 1.0
	v_fmaak_f32 v38, v36, v38, 0x3d2aaaab
	v_fmaak_f32 v38, v36, v38, 0x3e2aaaab
	v_mul_f32_e64 v28, v28, -v37
	v_fma_f32 v38, v36, v38, 0.5
	v_bfe_u32 v37, v28, 16, 1
	v_fma_f32 v38, v36, v38, 1.0
	v_add3_u32 v28, v28, v37, s71
	v_div_fixup_f32 v24, v35, v24, 1.0
	ds_read_u16 v35, v136 offset:32
	ds_write_b16_d16_hi v116, v28 offset:17440
	v_mul_f32_e64 v28, v36, -v38
	v_max_f32_e32 v28, 0, v28
	v_sqrt_f32_e32 v28, v28
	s_waitcnt lgkmcnt(1)
; DEV float bf2f(u16 h) { return __uint_as_float(((unsigned)h) << 16); }
; DEV float sigmoidf_(float x) { return 1.f / (1.f + __expf(-x)); }
; PHASE void lru_phase(const Params& p, int layer, const u16* __restrict__ GC, u16* __restrict__ OC, float* __restrict__ LA, ...
;     ...
;         for (int mi = 0; mi < 4; ++mi)
; #pragma unroll
;           for (int j = 0; j < 4; ++j) {
;             const int t = mi * 16 + fq * 4 + j;
;             const float rr = sigmoidf_(aR[mi][ni][j] + bba);
;             const float gg = sigmoidf_(aG[mi][ni][j] + bbx);
;             const float xv = bf2f(sX[t * 136 + col]);
;             const float la = -c8 * rr;
;             const float l2 = la + la;
;             const float e1 = la * (1.f + la * (0.5f + la * (0.16666667f + la * (0.041666668f + la * (0.0083333338f + la * 0.0013888889f)))));
;             const float e2 = l2 * (1.f + l2 * (0.5f + l2 * (0.16666667f + l2 * (0.041666668f + l2 * (0.0083333338f + l2 * (0.0013888889f + l2 * 0.0001984127f))))));
;             sR[t * 128 + col] = f2bf(-e1);
;             sG[t * 128 + col] = f2bf(__builtin_amdgcn_sqrtf(fmaxf(-e2, 0.f)) * gg * xv);
;           }
	v_lshlrev_b32_e32 v35, 16, v35
	v_add_f32_e32 v25, 1.0, v25
	v_add_f32_e32 v20, v20, v33
	v_mul_f32_e32 v24, v24, v28
	v_mul_f32_e32 v24, v24, v35
	v_bfe_u32 v28, v24, 16, 1
	v_add3_u32 v24, v24, v28, s71
	ds_write_b16_d16_hi v116, v24 offset:33824
	v_add_f32_e32 v24, v29, v33
	v_mul_f32_e32 v24, 0xbfb8aa3b, v24
	v_exp_f32_e32 v24, v24
	v_mul_f32_e32 v20, 0xbfb8aa3b, v20
	v_exp_f32_e32 v20, v20
	v_add_f32_e32 v16, v16, v32
	v_add_f32_e32 v24, 1.0, v24
	v_div_scale_f32 v28, s[0:1], v24, v24, 1.0
	v_rcp_f32_e32 v29, v28
	v_add_f32_e32 v20, 1.0, v20
	v_mul_f32_e32 v16, 0xbfb8aa3b, v16
	v_exp_f32_e32 v16, v16
	v_fma_f32 v35, -v28, v29, 1.0
	v_fmac_f32_e32 v29, v35, v29
	v_div_scale_f32 v35, vcc, 1.0, v24, 1.0
	v_mul_f32_e32 v36, v35, v29
	v_fma_f32 v37, -v28, v36, v35
	v_fmac_f32_e32 v36, v37, v29
	v_fma_f32 v28, -v28, v36, v35
	v_div_fmas_f32 v28, v28, v29, v36
	v_div_fixup_f32 v24, v28, v24, 1.0
	v_div_scale_f32 v28, s[0:1], v25, v25, 1.0
	v_rcp_f32_e32 v29, v28
	v_mul_f32_e32 v24, v24, v34
	v_add_f32_e32 v16, 1.0, v16
	v_add_f32_e32 v17, v17, v32
	v_fma_f32 v35, -v28, v29, 1.0
	v_fmac_f32_e32 v29, v35, v29
	v_div_scale_f32 v35, vcc, 1.0, v25, 1.0
	v_mul_f32_e32 v36, v35, v29
	v_fma_f32 v37, -v28, v36, v35
	v_fmac_f32_e32 v36, v37, v29
	v_fma_f32 v28, -v28, v36, v35
	v_fmamk_f32 v35, v24, 0x3ab60b61, v181
	v_div_fmas_f32 v28, v28, v29, v36
	v_add_f32_e32 v29, v24, v24
	v_fmaak_f32 v35, v24, v35, 0x3d2aaaab
	v_fmaak_f32 v35, v24, v35, 0x3e2aaaab
	v_fmamk_f32 v36, v29, 0x39500d01, v191
	v_fma_f32 v35, v24, v35, 0.5
	v_fmaak_f32 v36, v29, v36, 0x3c088889
	v_fma_f32 v35, v24, v35, 1.0
	v_fmaak_f32 v36, v29, v36, 0x3d2aaaab
	v_fmaak_f32 v36, v29, v36, 0x3e2aaaab
	v_mul_f32_e64 v24, v24, -v35
	v_fma_f32 v36, v29, v36, 0.5
	v_bfe_u32 v35, v24, 16, 1
	v_fma_f32 v36, v29, v36, 1.0
	v_add3_u32 v24, v24, v35, s71
	v_div_fixup_f32 v25, v28, v25, 1.0
	ds_read_u16 v28, v137 offset:32
	ds_write_b16_d16_hi v117, v24 offset:17440
	v_mul_f32_e64 v24, v29, -v36
	v_max_f32_e32 v24, 0, v24
	v_sqrt_f32_e32 v24, v24
	s_waitcnt lgkmcnt(1)
	v_lshlrev_b32_e32 v28, 16, v28
	v_mul_f32_e32 v17, 0xbfb8aa3b, v17
	v_exp_f32_e32 v17, v17
	v_mul_f32_e32 v24, v25, v24
	v_mul_f32_e32 v24, v24, v28
	v_bfe_u32 v25, v24, 16, 1
	v_add3_u32 v24, v24, v25, s71
	ds_write_b16_d16_hi v117, v24 offset:33824
	v_add_f32_e32 v24, v30, v33
	v_mul_f32_e32 v24, 0xbfb8aa3b, v24
	v_exp_f32_e32 v24, v24
	v_add_f32_e32 v17, 1.0, v17
	v_add_f32_e32 v12, v12, v33
	v_mul_f32_e32 v12, 0xbfb8aa3b, v12
	v_add_f32_e32 v24, 1.0, v24
	v_div_scale_f32 v25, s[0:1], v24, v24, 1.0
	v_rcp_f32_e32 v28, v25
	v_exp_f32_e32 v12, v12
	v_add_f32_e32 v8, v8, v32
	v_mul_f32_e32 v8, 0xbfb8aa3b, v8
	v_fma_f32 v29, -v25, v28, 1.0
	v_fmac_f32_e32 v28, v29, v28
	v_div_scale_f32 v29, vcc, 1.0, v24, 1.0
	v_mul_f32_e32 v30, v29, v28
	v_fma_f32 v35, -v25, v30, v29
	v_fmac_f32_e32 v30, v35, v28
	v_fma_f32 v25, -v25, v30, v29
	v_div_fmas_f32 v25, v25, v28, v30
	v_div_fixup_f32 v24, v25, v24, 1.0
	v_add_f32_e32 v25, v26, v32
	v_mul_f32_e32 v25, 0xbfb8aa3b, v25
	v_exp_f32_e32 v25, v25
	v_mul_f32_e32 v24, v24, v34
	v_add_f32_e32 v12, 1.0, v12
	v_exp_f32_e32 v8, v8
	v_add_f32_e32 v25, 1.0, v25
	v_div_scale_f32 v26, s[0:1], v25, v25, 1.0
	v_rcp_f32_e32 v28, v26
	v_add_f32_e32 v8, 1.0, v8
	v_add_f32_e32 v9, v9, v32
	v_mul_f32_e32 v9, 0xbfb8aa3b, v9
	v_fma_f32 v29, -v26, v28, 1.0
	v_fmac_f32_e32 v28, v29, v28
	v_div_scale_f32 v29, vcc, 1.0, v25, 1.0
	v_mul_f32_e32 v30, v29, v28
	v_fma_f32 v35, -v26, v30, v29
	v_fmac_f32_e32 v30, v35, v28
	v_fma_f32 v26, -v26, v30, v29
	v_fmamk_f32 v29, v24, 0x3ab60b61, v181
	v_div_fmas_f32 v26, v26, v28, v30
	v_add_f32_e32 v28, v24, v24
	v_fmaak_f32 v29, v24, v29, 0x3d2aaaab
	v_fmaak_f32 v29, v24, v29, 0x3e2aaaab
	v_fmamk_f32 v30, v28, 0x39500d01, v191
	v_fma_f32 v29, v24, v29, 0.5
	v_fmaak_f32 v30, v28, v30, 0x3c088889
	v_fma_f32 v29, v24, v29, 1.0
	v_fmaak_f32 v30, v28, v30, 0x3d2aaaab
	v_fmaak_f32 v30, v28, v30, 0x3e2aaaab
	v_mul_f32_e64 v24, v24, -v29
	v_fma_f32 v30, v28, v30, 0.5
	v_bfe_u32 v29, v24, 16, 1
	v_fma_f32 v30, v28, v30, 1.0
	v_add3_u32 v24, v24, v29, s71
	v_div_fixup_f32 v25, v26, v25, 1.0
	ds_read_u16 v26, v137 offset:304
	ds_write_b16_d16_hi v118, v24 offset:17440
	v_mul_f32_e64 v24, v28, -v30
	v_max_f32_e32 v24, 0, v24
	v_sqrt_f32_e32 v24, v24
	s_waitcnt lgkmcnt(1)
	v_lshlrev_b32_e32 v26, 16, v26
	v_exp_f32_e32 v9, v9
	v_add_f32_e32 v4, v4, v33
	v_mul_f32_e32 v24, v25, v24
	v_mul_f32_e32 v24, v24, v26
	v_bfe_u32 v25, v24, 16, 1
	v_add3_u32 v24, v24, v25, s71
	ds_write_b16_d16_hi v118, v24 offset:33824
	v_add_f32_e32 v24, v31, v33
	v_mul_f32_e32 v24, 0xbfb8aa3b, v24
	v_exp_f32_e32 v24, v24
	v_add_f32_e32 v9, 1.0, v9
	v_mul_f32_e32 v4, 0xbfb8aa3b, v4
	v_exp_f32_e32 v4, v4
	v_add_f32_e32 v24, 1.0, v24
	v_div_scale_f32 v25, s[0:1], v24, v24, 1.0
	v_rcp_f32_e32 v26, v25
	v_add_f32_e32 v4, 1.0, v4
	v_add_f32_e32 v0, v0, v32
	v_mul_f32_e32 v0, 0xbfb8aa3b, v0
	v_fma_f32 v28, -v25, v26, 1.0
	v_fmac_f32_e32 v26, v28, v26
	v_div_scale_f32 v28, vcc, 1.0, v24, 1.0
	v_mul_f32_e32 v29, v28, v26
	v_fma_f32 v30, -v25, v29, v28
	v_fmac_f32_e32 v29, v30, v26
	v_fma_f32 v25, -v25, v29, v28
	v_div_fmas_f32 v25, v25, v26, v29
	v_div_fixup_f32 v24, v25, v24, 1.0
	v_add_f32_e32 v25, v27, v32
	v_mul_f32_e32 v25, 0xbfb8aa3b, v25
	v_exp_f32_e32 v25, v25
	v_mul_f32_e32 v24, v24, v34
	v_exp_f32_e32 v0, v0
	v_add_f32_e32 v1, v1, v32
	v_add_f32_e32 v25, 1.0, v25
	v_div_scale_f32 v26, s[0:1], v25, v25, 1.0
	v_rcp_f32_e32 v27, v26
	v_add_f32_e32 v0, 1.0, v0
	v_mul_f32_e32 v1, 0xbfb8aa3b, v1
	v_exp_f32_e32 v1, v1
	v_fma_f32 v28, -v26, v27, 1.0
	v_fmac_f32_e32 v27, v28, v27
	v_div_scale_f32 v28, vcc, 1.0, v25, 1.0
	v_mul_f32_e32 v29, v28, v27
	v_fma_f32 v30, -v26, v29, v28
	v_fmac_f32_e32 v29, v30, v27
	v_fma_f32 v26, -v26, v29, v28
	v_fmamk_f32 v28, v24, 0x3ab60b61, v181
	v_div_fmas_f32 v26, v26, v27, v29
	v_add_f32_e32 v27, v24, v24
	v_fmaak_f32 v28, v24, v28, 0x3d2aaaab
	v_fmaak_f32 v28, v24, v28, 0x3e2aaaab
	v_fmamk_f32 v29, v27, 0x39500d01, v191
	v_fma_f32 v28, v24, v28, 0.5
	v_fmaak_f32 v29, v27, v29, 0x3c088889
	v_fma_f32 v28, v24, v28, 1.0
	v_fmaak_f32 v29, v27, v29, 0x3d2aaaab
	v_fmaak_f32 v29, v27, v29, 0x3e2aaaab
	v_mul_f32_e64 v24, v24, -v28
	v_fma_f32 v29, v27, v29, 0.5
	v_bfe_u32 v28, v24, 16, 1
	v_fma_f32 v29, v27, v29, 1.0
	v_add3_u32 v24, v24, v28, s71
	v_div_fixup_f32 v25, v26, v25, 1.0
	ds_read_u16 v26, v137 offset:576
	ds_write_b16_d16_hi v119, v24 offset:17440
	v_mul_f32_e64 v24, v27, -v29
	v_max_f32_e32 v24, 0, v24
	v_sqrt_f32_e32 v24, v24
	s_waitcnt lgkmcnt(1)
; DEV float bf2f(u16 h) { return __uint_as_float(((unsigned)h) << 16); }
; DEV float sigmoidf_(float x) { return 1.f / (1.f + __expf(-x)); }
; PHASE void lru_phase(const Params& p, int layer, const u16* __restrict__ GC, u16* __restrict__ OC, float* __restrict__ LA, ...
;     ...
;         for (int mi = 0; mi < 4; ++mi)
; #pragma unroll
;           for (int j = 0; j < 4; ++j) {
;             const int t = mi * 16 + fq * 4 + j;
;             const float rr = sigmoidf_(aR[mi][ni][j] + bba);
;             const float gg = sigmoidf_(aG[mi][ni][j] + bbx);
;             const float xv = bf2f(sX[t * 136 + col]);
;             const float la = -c8 * rr;
;             const float l2 = la + la;
;             const float e1 = la * (1.f + la * (0.5f + la * (0.16666667f + la * (0.041666668f + la * (0.0083333338f + la * 0.0013888889f)))));
;             const float e2 = l2 * (1.f + l2 * (0.5f + l2 * (0.16666667f + l2 * (0.041666668f + l2 * (0.0083333338f + l2 * (0.0013888889f + l2 * 0.0001984127f))))));
;             sR[t * 128 + col] = f2bf(-e1);
;             sG[t * 128 + col] = f2bf(__builtin_amdgcn_sqrtf(fmaxf(-e2, 0.f)) * gg * xv);
;           }
	v_lshlrev_b32_e32 v26, 16, v26
	v_add_f32_e32 v1, 1.0, v1
	s_mov_b64 s[26:27], 0
	v_mul_f32_e32 v24, v25, v24
	v_mul_f32_e32 v24, v24, v26
	v_bfe_u32 v25, v24, 16, 1
	v_add3_u32 v24, v24, v25, s71
	ds_write_b16_d16_hi v119, v24 offset:33824
	v_div_scale_f32 v24, s[0:1], v20, v20, 1.0
	v_rcp_f32_e32 v25, v24
	s_nop 0
	v_fma_f32 v26, -v24, v25, 1.0
	v_fmac_f32_e32 v25, v26, v25
	v_div_scale_f32 v26, vcc, 1.0, v20, 1.0
	v_mul_f32_e32 v27, v26, v25
	v_fma_f32 v28, -v24, v27, v26
	v_fmac_f32_e32 v27, v28, v25
	v_fma_f32 v24, -v24, v27, v26
	v_div_fmas_f32 v24, v24, v25, v27
	v_div_fixup_f32 v20, v24, v20, 1.0
	v_div_scale_f32 v24, s[0:1], v16, v16, 1.0
	v_rcp_f32_e32 v25, v24
	v_mul_f32_e32 v20, v20, v34
	v_fma_f32 v26, -v24, v25, 1.0
	v_fmac_f32_e32 v25, v26, v25
	v_div_scale_f32 v26, vcc, 1.0, v16, 1.0
	v_mul_f32_e32 v27, v26, v25
	v_fma_f32 v28, -v24, v27, v26
	v_fmac_f32_e32 v27, v28, v25
	v_fma_f32 v24, -v24, v27, v26
	v_fmamk_f32 v26, v20, 0x3ab60b61, v181
	v_div_fmas_f32 v24, v24, v25, v27
	v_add_f32_e32 v25, v20, v20
	v_fmaak_f32 v26, v20, v26, 0x3d2aaaab
	v_fmaak_f32 v26, v20, v26, 0x3e2aaaab
	v_fmamk_f32 v27, v25, 0x39500d01, v191
	v_fma_f32 v26, v20, v26, 0.5
	v_fmaak_f32 v27, v25, v27, 0x3c088889
	v_fma_f32 v26, v20, v26, 1.0
	v_fmaak_f32 v27, v25, v27, 0x3d2aaaab
	v_fmaak_f32 v27, v25, v27, 0x3e2aaaab
	v_mul_f32_e64 v20, v20, -v26
	v_fma_f32 v27, v25, v27, 0.5
	v_bfe_u32 v26, v20, 16, 1
	v_fma_f32 v27, v25, v27, 1.0
	v_add3_u32 v20, v20, v26, s71
	v_div_fixup_f32 v16, v24, v16, 1.0
	ds_read_u16 v24, v137 offset:4112
	ds_write_b16_d16_hi v120, v20 offset:17440
	v_mul_f32_e64 v20, v25, -v27
	v_max_f32_e32 v20, 0, v20
	v_sqrt_f32_e32 v20, v20
	s_waitcnt lgkmcnt(1)
	v_lshlrev_b32_e32 v24, 16, v24
	v_mul_f32_e32 v16, v16, v20
	v_mul_f32_e32 v16, v16, v24
	v_bfe_u32 v20, v16, 16, 1
	v_add3_u32 v16, v16, v20, s71
	ds_write_b16_d16_hi v120, v16 offset:33824
	v_add_f32_e32 v16, v21, v33
	v_mul_f32_e32 v16, 0xbfb8aa3b, v16
	v_exp_f32_e32 v16, v16
	s_nop 0
	v_add_f32_e32 v16, 1.0, v16
	v_div_scale_f32 v20, s[0:1], v16, v16, 1.0
	v_rcp_f32_e32 v21, v20
	s_nop 0
	v_fma_f32 v24, -v20, v21, 1.0
	v_fmac_f32_e32 v21, v24, v21
	v_div_scale_f32 v24, vcc, 1.0, v16, 1.0
	v_mul_f32_e32 v25, v24, v21
	v_fma_f32 v26, -v20, v25, v24
	v_fmac_f32_e32 v25, v26, v21
	v_fma_f32 v20, -v20, v25, v24
	v_div_fmas_f32 v20, v20, v21, v25
	v_div_fixup_f32 v16, v20, v16, 1.0
	v_div_scale_f32 v20, s[0:1], v17, v17, 1.0
	v_rcp_f32_e32 v21, v20
	v_mul_f32_e32 v16, v16, v34
	v_fma_f32 v24, -v20, v21, 1.0
	v_fmac_f32_e32 v21, v24, v21
	v_div_scale_f32 v24, vcc, 1.0, v17, 1.0
	v_mul_f32_e32 v25, v24, v21
	v_fma_f32 v26, -v20, v25, v24
	v_fmac_f32_e32 v25, v26, v21
	v_fma_f32 v20, -v20, v25, v24
	v_fmamk_f32 v24, v16, 0x3ab60b61, v181
	v_div_fmas_f32 v20, v20, v21, v25
	v_add_f32_e32 v21, v16, v16
	v_fmaak_f32 v24, v16, v24, 0x3d2aaaab
	v_fmaak_f32 v24, v16, v24, 0x3e2aaaab
	v_fmamk_f32 v25, v21, 0x39500d01, v191
	v_fma_f32 v24, v16, v24, 0.5
	v_fmaak_f32 v25, v21, v25, 0x3c088889
	v_fma_f32 v24, v16, v24, 1.0
	v_fmaak_f32 v25, v21, v25, 0x3d2aaaab
	v_fmaak_f32 v25, v21, v25, 0x3e2aaaab
	v_mul_f32_e64 v16, v16, -v24
	v_fma_f32 v25, v21, v25, 0.5
	v_bfe_u32 v24, v16, 16, 1
	v_fma_f32 v25, v21, v25, 1.0
	v_add3_u32 v16, v16, v24, s71
	v_div_fixup_f32 v17, v20, v17, 1.0
	ds_read_u16 v20, v137 offset:4384
	ds_write_b16_d16_hi v121, v16 offset:17440
	v_mul_f32_e64 v16, v21, -v25
	v_max_f32_e32 v16, 0, v16
	v_sqrt_f32_e32 v16, v16
	s_waitcnt lgkmcnt(1)
	v_lshlrev_b32_e32 v20, 16, v20
	v_mul_f32_e32 v16, v17, v16
	v_mul_f32_e32 v16, v16, v20
	v_bfe_u32 v17, v16, 16, 1
	v_add3_u32 v16, v16, v17, s71
	ds_write_b16_d16_hi v121, v16 offset:33824
	v_add_f32_e32 v16, v22, v33
	v_mul_f32_e32 v16, 0xbfb8aa3b, v16
	v_exp_f32_e32 v16, v16
	s_nop 0
	v_add_f32_e32 v16, 1.0, v16
	v_div_scale_f32 v17, s[0:1], v16, v16, 1.0
	v_rcp_f32_e32 v20, v17
	s_nop 0
	v_fma_f32 v21, -v17, v20, 1.0
	v_fmac_f32_e32 v20, v21, v20
	v_div_scale_f32 v21, vcc, 1.0, v16, 1.0
	v_mul_f32_e32 v22, v21, v20
	v_fma_f32 v24, -v17, v22, v21
	v_fmac_f32_e32 v22, v24, v20
	v_fma_f32 v17, -v17, v22, v21
	v_div_fmas_f32 v17, v17, v20, v22
	v_div_fixup_f32 v16, v17, v16, 1.0
	v_add_f32_e32 v17, v18, v32
	v_mul_f32_e32 v17, 0xbfb8aa3b, v17
	v_exp_f32_e32 v17, v17
	v_mul_f32_e32 v16, v16, v34
	v_add_f32_e32 v17, 1.0, v17
	v_div_scale_f32 v18, s[0:1], v17, v17, 1.0
	v_rcp_f32_e32 v20, v18
	s_nop 0
	v_fma_f32 v21, -v18, v20, 1.0
	v_fmac_f32_e32 v20, v21, v20
	v_div_scale_f32 v21, vcc, 1.0, v17, 1.0
	v_mul_f32_e32 v22, v21, v20
	v_fma_f32 v24, -v18, v22, v21
	v_fmac_f32_e32 v22, v24, v20
	v_fma_f32 v18, -v18, v22, v21
	v_fmamk_f32 v21, v16, 0x3ab60b61, v181
	v_div_fmas_f32 v18, v18, v20, v22
	v_add_f32_e32 v20, v16, v16
	v_fmaak_f32 v21, v16, v21, 0x3d2aaaab
	v_fmaak_f32 v21, v16, v21, 0x3e2aaaab
	v_fmamk_f32 v22, v20, 0x39500d01, v191
	v_fma_f32 v21, v16, v21, 0.5
	v_fmaak_f32 v22, v20, v22, 0x3c088889
	v_fma_f32 v21, v16, v21, 1.0
	v_fmaak_f32 v22, v20, v22, 0x3d2aaaab
	v_fmaak_f32 v22, v20, v22, 0x3e2aaaab
	v_mul_f32_e64 v16, v16, -v21
	v_fma_f32 v22, v20, v22, 0.5
	v_bfe_u32 v21, v16, 16, 1
	v_fma_f32 v22, v20, v22, 1.0
	v_add3_u32 v16, v16, v21, s71
	v_div_fixup_f32 v17, v18, v17, 1.0
	ds_read_u16 v18, v137 offset:4656
	ds_write_b16_d16_hi v122, v16 offset:17440
	v_mul_f32_e64 v16, v20, -v22
	v_max_f32_e32 v16, 0, v16
	v_sqrt_f32_e32 v16, v16
	s_waitcnt lgkmcnt(1)
; DEV float bf2f(u16 h) { return __uint_as_float(((unsigned)h) << 16); }
; DEV float sigmoidf_(float x) { return 1.f / (1.f + __expf(-x)); }
; PHASE void lru_phase(const Params& p, int layer, const u16* __restrict__ GC, u16* __restrict__ OC, float* __restrict__ LA, ...
;     ...
;         for (int mi = 0; mi < 4; ++mi)
; #pragma unroll
;           for (int j = 0; j < 4; ++j) {
;             const int t = mi * 16 + fq * 4 + j;
;             const float rr = sigmoidf_(aR[mi][ni][j] + bba);
;             const float gg = sigmoidf_(aG[mi][ni][j] + bbx);
;             const float xv = bf2f(sX[t * 136 + col]);
;             const float la = -c8 * rr;
;             const float l2 = la + la;
;             const float e1 = la * (1.f + la * (0.5f + la * (0.16666667f + la * (0.041666668f + la * (0.0083333338f + la * 0.0013888889f)))));
;             const float e2 = l2 * (1.f + l2 * (0.5f + l2 * (0.16666667f + l2 * (0.041666668f + l2 * (0.0083333338f + l2 * (0.0013888889f + l2 * 0.0001984127f))))));
;             sR[t * 128 + col] = f2bf(-e1);
;             sG[t * 128 + col] = f2bf(__builtin_amdgcn_sqrtf(fmaxf(-e2, 0.f)) * gg * xv);
;           }
	v_lshlrev_b32_e32 v18, 16, v18
	v_mul_f32_e32 v16, v17, v16
	v_mul_f32_e32 v16, v16, v18
	v_bfe_u32 v17, v16, 16, 1
	v_add3_u32 v16, v16, v17, s71
	ds_write_b16_d16_hi v122, v16 offset:33824
	v_add_f32_e32 v16, v23, v33
	v_mul_f32_e32 v16, 0xbfb8aa3b, v16
	v_exp_f32_e32 v16, v16
	s_nop 0
	v_add_f32_e32 v16, 1.0, v16
	v_div_scale_f32 v17, s[0:1], v16, v16, 1.0
	v_rcp_f32_e32 v18, v17
	s_nop 0
	v_fma_f32 v20, -v17, v18, 1.0
	v_fmac_f32_e32 v18, v20, v18
	v_div_scale_f32 v20, vcc, 1.0, v16, 1.0
	v_mul_f32_e32 v21, v20, v18
	v_fma_f32 v22, -v17, v21, v20
	v_fmac_f32_e32 v21, v22, v18
	v_fma_f32 v17, -v17, v21, v20
	v_div_fmas_f32 v17, v17, v18, v21
	v_div_fixup_f32 v16, v17, v16, 1.0
	v_add_f32_e32 v17, v19, v32
	v_mul_f32_e32 v17, 0xbfb8aa3b, v17
	v_exp_f32_e32 v17, v17
	v_mul_f32_e32 v16, v16, v34
	v_add_f32_e32 v17, 1.0, v17
	v_div_scale_f32 v18, s[0:1], v17, v17, 1.0
	v_rcp_f32_e32 v19, v18
	s_nop 0
	v_fma_f32 v20, -v18, v19, 1.0
	v_fmac_f32_e32 v19, v20, v19
	v_div_scale_f32 v20, vcc, 1.0, v17, 1.0
	v_mul_f32_e32 v21, v20, v19
	v_fma_f32 v22, -v18, v21, v20
	v_fmac_f32_e32 v21, v22, v19
	v_fma_f32 v18, -v18, v21, v20
	v_fmamk_f32 v20, v16, 0x3ab60b61, v181
	v_div_fmas_f32 v18, v18, v19, v21
	v_add_f32_e32 v19, v16, v16
	v_fmaak_f32 v20, v16, v20, 0x3d2aaaab
	v_fmaak_f32 v20, v16, v20, 0x3e2aaaab
	v_fmamk_f32 v21, v19, 0x39500d01, v191
	v_fma_f32 v20, v16, v20, 0.5
	v_fmaak_f32 v21, v19, v21, 0x3c088889
	v_fma_f32 v20, v16, v20, 1.0
	v_fmaak_f32 v21, v19, v21, 0x3d2aaaab
	v_fmaak_f32 v21, v19, v21, 0x3e2aaaab
	v_mul_f32_e64 v16, v16, -v20
	v_fma_f32 v21, v19, v21, 0.5
	v_bfe_u32 v20, v16, 16, 1
	v_fma_f32 v21, v19, v21, 1.0
	v_add3_u32 v16, v16, v20, s71
	v_div_fixup_f32 v17, v18, v17, 1.0
	ds_read_u16 v18, v137 offset:4928
	ds_write_b16_d16_hi v123, v16 offset:17440
	v_mul_f32_e64 v16, v19, -v21
	v_max_f32_e32 v16, 0, v16
	v_sqrt_f32_e32 v16, v16
	s_waitcnt lgkmcnt(1)
	v_lshlrev_b32_e32 v18, 16, v18
	v_mul_f32_e32 v16, v17, v16
	v_mul_f32_e32 v16, v16, v18
	v_bfe_u32 v17, v16, 16, 1
	v_add3_u32 v16, v16, v17, s71
	ds_write_b16_d16_hi v123, v16 offset:33824
	v_div_scale_f32 v16, s[0:1], v12, v12, 1.0
	v_rcp_f32_e32 v17, v16
	s_nop 0
	v_fma_f32 v18, -v16, v17, 1.0
	v_fmac_f32_e32 v17, v18, v17
	v_div_scale_f32 v18, vcc, 1.0, v12, 1.0
	v_mul_f32_e32 v19, v18, v17
	v_fma_f32 v20, -v16, v19, v18
	v_fmac_f32_e32 v19, v20, v17
	v_fma_f32 v16, -v16, v19, v18
	v_div_fmas_f32 v16, v16, v17, v19
	v_div_fixup_f32 v12, v16, v12, 1.0
	v_div_scale_f32 v16, s[0:1], v8, v8, 1.0
	v_rcp_f32_e32 v17, v16
	v_mul_f32_e32 v12, v12, v34
	v_fma_f32 v18, -v16, v17, 1.0
	v_fmac_f32_e32 v17, v18, v17
	v_div_scale_f32 v18, vcc, 1.0, v8, 1.0
	v_mul_f32_e32 v19, v18, v17
	v_fma_f32 v20, -v16, v19, v18
	v_fmac_f32_e32 v19, v20, v17
	v_fma_f32 v16, -v16, v19, v18
	v_fmamk_f32 v18, v12, 0x3ab60b61, v181
	v_div_fmas_f32 v16, v16, v17, v19
	v_add_f32_e32 v17, v12, v12
	v_fmaak_f32 v18, v12, v18, 0x3d2aaaab
	v_fmaak_f32 v18, v12, v18, 0x3e2aaaab
	v_fmamk_f32 v19, v17, 0x39500d01, v191
	v_fma_f32 v18, v12, v18, 0.5
	v_fmaak_f32 v19, v17, v19, 0x3c088889
	v_fma_f32 v18, v12, v18, 1.0
	v_fmaak_f32 v19, v17, v19, 0x3d2aaaab
	v_fmaak_f32 v19, v17, v19, 0x3e2aaaab
	v_mul_f32_e64 v12, v12, -v18
	v_fma_f32 v19, v17, v19, 0.5
	v_bfe_u32 v18, v12, 16, 1
	v_fma_f32 v19, v17, v19, 1.0
	v_add3_u32 v12, v12, v18, s71
	v_div_fixup_f32 v8, v16, v8, 1.0
	ds_read_u16 v16, v137 offset:8464
	ds_write_b16_d16_hi v124, v12 offset:17440
	v_mul_f32_e64 v12, v17, -v19
	v_max_f32_e32 v12, 0, v12
	v_sqrt_f32_e32 v12, v12
	s_waitcnt lgkmcnt(1)
	v_lshlrev_b32_e32 v16, 16, v16
	v_mul_f32_e32 v8, v8, v12
	v_mul_f32_e32 v8, v8, v16
	v_bfe_u32 v12, v8, 16, 1
	v_add3_u32 v8, v8, v12, s71
	ds_write_b16_d16_hi v124, v8 offset:33824
	v_add_f32_e32 v8, v13, v33
	v_mul_f32_e32 v8, 0xbfb8aa3b, v8
	v_exp_f32_e32 v8, v8
	s_nop 0
	v_add_f32_e32 v8, 1.0, v8
	v_div_scale_f32 v12, s[0:1], v8, v8, 1.0
	v_rcp_f32_e32 v13, v12
	s_nop 0
	v_fma_f32 v16, -v12, v13, 1.0
	v_fmac_f32_e32 v13, v16, v13
	v_div_scale_f32 v16, vcc, 1.0, v8, 1.0
	v_mul_f32_e32 v17, v16, v13
	v_fma_f32 v18, -v12, v17, v16
	v_fmac_f32_e32 v17, v18, v13
	v_fma_f32 v12, -v12, v17, v16
	v_div_fmas_f32 v12, v12, v13, v17
	v_div_fixup_f32 v8, v12, v8, 1.0
	v_div_scale_f32 v12, s[0:1], v9, v9, 1.0
	v_rcp_f32_e32 v13, v12
	v_mul_f32_e32 v8, v8, v34
	v_fma_f32 v16, -v12, v13, 1.0
	v_fmac_f32_e32 v13, v16, v13
	v_div_scale_f32 v16, vcc, 1.0, v9, 1.0
	v_mul_f32_e32 v17, v16, v13
	v_fma_f32 v18, -v12, v17, v16
	v_fmac_f32_e32 v17, v18, v13
	v_fma_f32 v12, -v12, v17, v16
	v_fmamk_f32 v16, v8, 0x3ab60b61, v181
	v_div_fmas_f32 v12, v12, v13, v17
	v_add_f32_e32 v13, v8, v8
	v_fmaak_f32 v16, v8, v16, 0x3d2aaaab
	v_fmaak_f32 v16, v8, v16, 0x3e2aaaab
	v_fmamk_f32 v17, v13, 0x39500d01, v191
	v_fma_f32 v16, v8, v16, 0.5
	v_fmaak_f32 v17, v13, v17, 0x3c088889
	v_fma_f32 v16, v8, v16, 1.0
	v_fmaak_f32 v17, v13, v17, 0x3d2aaaab
	v_fmaak_f32 v17, v13, v17, 0x3e2aaaab
	v_mul_f32_e64 v8, v8, -v16
	v_fma_f32 v17, v13, v17, 0.5
	v_bfe_u32 v16, v8, 16, 1
	v_fma_f32 v17, v13, v17, 1.0
	v_add3_u32 v8, v8, v16, s71
	v_div_fixup_f32 v9, v12, v9, 1.0
	ds_read_u16 v12, v137 offset:8736
	ds_write_b16_d16_hi v125, v8 offset:17440
	v_mul_f32_e64 v8, v13, -v17
	v_max_f32_e32 v8, 0, v8
	v_sqrt_f32_e32 v8, v8
	s_waitcnt lgkmcnt(1)
; DEV float bf2f(u16 h) { return __uint_as_float(((unsigned)h) << 16); }
; DEV float sigmoidf_(float x) { return 1.f / (1.f + __expf(-x)); }
; PHASE void lru_phase(const Params& p, int layer, const u16* __restrict__ GC, u16* __restrict__ OC, float* __restrict__ LA, ...
;     ...
;         for (int mi = 0; mi < 4; ++mi)
; #pragma unroll
;           for (int j = 0; j < 4; ++j) {
;             const int t = mi * 16 + fq * 4 + j;
;             const float rr = sigmoidf_(aR[mi][ni][j] + bba);
;             const float gg = sigmoidf_(aG[mi][ni][j] + bbx);
;             const float xv = bf2f(sX[t * 136 + col]);
;             const float la = -c8 * rr;
;             const float l2 = la + la;
;             const float e1 = la * (1.f + la * (0.5f + la * (0.16666667f + la * (0.041666668f + la * (0.0083333338f + la * 0.0013888889f)))));
;             const float e2 = l2 * (1.f + l2 * (0.5f + l2 * (0.16666667f + l2 * (0.041666668f + l2 * (0.0083333338f + l2 * (0.0013888889f + l2 * 0.0001984127f))))));
;             sR[t * 128 + col] = f2bf(-e1);
;             sG[t * 128 + col] = f2bf(__builtin_amdgcn_sqrtf(fmaxf(-e2, 0.f)) * gg * xv);
;           }
	v_lshlrev_b32_e32 v12, 16, v12
	v_mul_f32_e32 v8, v9, v8
	v_mul_f32_e32 v8, v8, v12
	v_bfe_u32 v9, v8, 16, 1
	v_add3_u32 v8, v8, v9, s71
	ds_write_b16_d16_hi v125, v8 offset:33824
	v_add_f32_e32 v8, v14, v33
	v_mul_f32_e32 v8, 0xbfb8aa3b, v8
	v_exp_f32_e32 v8, v8
	s_nop 0
	v_add_f32_e32 v8, 1.0, v8
	v_div_scale_f32 v9, s[0:1], v8, v8, 1.0
	v_rcp_f32_e32 v12, v9
	s_nop 0
	v_fma_f32 v13, -v9, v12, 1.0
	v_fmac_f32_e32 v12, v13, v12
	v_div_scale_f32 v13, vcc, 1.0, v8, 1.0
	v_mul_f32_e32 v14, v13, v12
	v_fma_f32 v16, -v9, v14, v13
	v_fmac_f32_e32 v14, v16, v12
	v_fma_f32 v9, -v9, v14, v13
	v_div_fmas_f32 v9, v9, v12, v14
	v_div_fixup_f32 v8, v9, v8, 1.0
	v_add_f32_e32 v9, v10, v32
	v_mul_f32_e32 v9, 0xbfb8aa3b, v9
	v_exp_f32_e32 v9, v9
	v_mul_f32_e32 v8, v8, v34
	v_add_f32_e32 v9, 1.0, v9
	v_div_scale_f32 v10, s[0:1], v9, v9, 1.0
	v_rcp_f32_e32 v12, v10
	s_nop 0
	v_fma_f32 v13, -v10, v12, 1.0
	v_fmac_f32_e32 v12, v13, v12
	v_div_scale_f32 v13, vcc, 1.0, v9, 1.0
	v_mul_f32_e32 v14, v13, v12
	v_fma_f32 v16, -v10, v14, v13
	v_fmac_f32_e32 v14, v16, v12
	v_fma_f32 v10, -v10, v14, v13
	v_fmamk_f32 v13, v8, 0x3ab60b61, v181
	v_div_fmas_f32 v10, v10, v12, v14
	v_add_f32_e32 v12, v8, v8
	v_fmaak_f32 v13, v8, v13, 0x3d2aaaab
	v_fmaak_f32 v13, v8, v13, 0x3e2aaaab
	v_fmamk_f32 v14, v12, 0x39500d01, v191
	v_fma_f32 v13, v8, v13, 0.5
	v_fmaak_f32 v14, v12, v14, 0x3c088889
	v_fma_f32 v13, v8, v13, 1.0
	v_fmaak_f32 v14, v12, v14, 0x3d2aaaab
	v_fmaak_f32 v14, v12, v14, 0x3e2aaaab
	v_mul_f32_e64 v8, v8, -v13
	v_fma_f32 v14, v12, v14, 0.5
	v_bfe_u32 v13, v8, 16, 1
	v_fma_f32 v14, v12, v14, 1.0
	v_add3_u32 v8, v8, v13, s71
	v_div_fixup_f32 v9, v10, v9, 1.0
	ds_read_u16 v10, v137 offset:9008
	ds_write_b16_d16_hi v126, v8 offset:17440
	v_mul_f32_e64 v8, v12, -v14
	v_max_f32_e32 v8, 0, v8
	v_sqrt_f32_e32 v8, v8
	s_waitcnt lgkmcnt(1)
	v_lshlrev_b32_e32 v10, 16, v10
	v_mul_f32_e32 v8, v9, v8
	v_mul_f32_e32 v8, v8, v10
	v_bfe_u32 v9, v8, 16, 1
	v_add3_u32 v8, v8, v9, s71
	ds_write_b16_d16_hi v126, v8 offset:33824
	v_add_f32_e32 v8, v15, v33
	v_mul_f32_e32 v8, 0xbfb8aa3b, v8
	v_exp_f32_e32 v8, v8
	s_nop 0
	v_add_f32_e32 v8, 1.0, v8
	v_div_scale_f32 v9, s[0:1], v8, v8, 1.0
	v_rcp_f32_e32 v10, v9
	s_nop 0
	v_fma_f32 v12, -v9, v10, 1.0
	v_fmac_f32_e32 v10, v12, v10
	v_div_scale_f32 v12, vcc, 1.0, v8, 1.0
	v_mul_f32_e32 v13, v12, v10
	v_fma_f32 v14, -v9, v13, v12
	v_fmac_f32_e32 v13, v14, v10
	v_fma_f32 v9, -v9, v13, v12
	v_div_fmas_f32 v9, v9, v10, v13
	v_div_fixup_f32 v8, v9, v8, 1.0
	v_add_f32_e32 v9, v11, v32
	v_mul_f32_e32 v9, 0xbfb8aa3b, v9
	v_exp_f32_e32 v9, v9
	v_mul_f32_e32 v8, v8, v34
	v_add_f32_e32 v9, 1.0, v9
	v_div_scale_f32 v10, s[0:1], v9, v9, 1.0
	v_rcp_f32_e32 v11, v10
	s_nop 0
	v_fma_f32 v12, -v10, v11, 1.0
	v_fmac_f32_e32 v11, v12, v11
	v_div_scale_f32 v12, vcc, 1.0, v9, 1.0
	v_mul_f32_e32 v13, v12, v11
	v_fma_f32 v14, -v10, v13, v12
	v_fmac_f32_e32 v13, v14, v11
	v_fma_f32 v10, -v10, v13, v12
	v_fmamk_f32 v12, v8, 0x3ab60b61, v181
	v_div_fmas_f32 v10, v10, v11, v13
	v_add_f32_e32 v11, v8, v8
	v_fmaak_f32 v12, v8, v12, 0x3d2aaaab
	v_fmaak_f32 v12, v8, v12, 0x3e2aaaab
	v_fmamk_f32 v13, v11, 0x39500d01, v191
	v_fma_f32 v12, v8, v12, 0.5
	v_fmaak_f32 v13, v11, v13, 0x3c088889
	v_fma_f32 v12, v8, v12, 1.0
	v_fmaak_f32 v13, v11, v13, 0x3d2aaaab
	v_fmaak_f32 v13, v11, v13, 0x3e2aaaab
	v_mul_f32_e64 v8, v8, -v12
	v_fma_f32 v13, v11, v13, 0.5
	v_bfe_u32 v12, v8, 16, 1
	v_fma_f32 v13, v11, v13, 1.0
	v_add3_u32 v8, v8, v12, s71
	v_div_fixup_f32 v9, v10, v9, 1.0
	ds_read_u16 v10, v137 offset:9280
	ds_write_b16_d16_hi v127, v8 offset:17440
	v_mul_f32_e64 v8, v11, -v13
	v_max_f32_e32 v8, 0, v8
	v_sqrt_f32_e32 v8, v8
	s_waitcnt lgkmcnt(1)
	v_lshlrev_b32_e32 v10, 16, v10
	v_mul_f32_e32 v8, v9, v8
	v_mul_f32_e32 v8, v8, v10
	v_bfe_u32 v9, v8, 16, 1
	v_add3_u32 v8, v8, v9, s71
	ds_write_b16_d16_hi v127, v8 offset:33824
	v_div_scale_f32 v8, s[0:1], v4, v4, 1.0
	v_rcp_f32_e32 v9, v8
	s_nop 0
	v_fma_f32 v10, -v8, v9, 1.0
	v_fmac_f32_e32 v9, v10, v9
	v_div_scale_f32 v10, vcc, 1.0, v4, 1.0
	v_mul_f32_e32 v11, v10, v9
	v_fma_f32 v12, -v8, v11, v10
	v_fmac_f32_e32 v11, v12, v9
	v_fma_f32 v8, -v8, v11, v10
	v_div_fmas_f32 v8, v8, v9, v11
	v_div_fixup_f32 v4, v8, v4, 1.0
	v_div_scale_f32 v8, s[0:1], v0, v0, 1.0
	v_rcp_f32_e32 v9, v8
	v_mul_f32_e32 v4, v4, v34
	v_fma_f32 v10, -v8, v9, 1.0
	v_fmac_f32_e32 v9, v10, v9
	v_div_scale_f32 v10, vcc, 1.0, v0, 1.0
	v_mul_f32_e32 v11, v10, v9
	v_fma_f32 v12, -v8, v11, v10
	v_fmac_f32_e32 v11, v12, v9
	v_fma_f32 v8, -v8, v11, v10
	v_fmamk_f32 v10, v4, 0x3ab60b61, v181
	v_div_fmas_f32 v8, v8, v9, v11
	v_add_f32_e32 v9, v4, v4
	v_fmaak_f32 v10, v4, v10, 0x3d2aaaab
	v_fmaak_f32 v10, v4, v10, 0x3e2aaaab
	v_fmamk_f32 v11, v9, 0x39500d01, v191
	v_fma_f32 v10, v4, v10, 0.5
	v_fmaak_f32 v11, v9, v11, 0x3c088889
	v_fma_f32 v10, v4, v10, 1.0
	v_fmaak_f32 v11, v9, v11, 0x3d2aaaab
	v_fmaak_f32 v11, v9, v11, 0x3e2aaaab
	v_mul_f32_e64 v4, v4, -v10
	v_fma_f32 v11, v9, v11, 0.5
	v_bfe_u32 v10, v4, 16, 1
	v_fma_f32 v11, v9, v11, 1.0
	v_add3_u32 v4, v4, v10, s71
	v_div_fixup_f32 v0, v8, v0, 1.0
	ds_read_u16 v8, v137 offset:12816
	ds_write_b16_d16_hi v128, v4 offset:17440
	v_mul_f32_e64 v4, v9, -v11
	v_max_f32_e32 v4, 0, v4
	v_sqrt_f32_e32 v4, v4
	s_waitcnt lgkmcnt(1)
; DEV float bf2f(u16 h) { return __uint_as_float(((unsigned)h) << 16); }
; DEV float sigmoidf_(float x) { return 1.f / (1.f + __expf(-x)); }
; PHASE void lru_phase(const Params& p, int layer, const u16* __restrict__ GC, u16* __restrict__ OC, float* __restrict__ LA, ...
;     ...
;         for (int mi = 0; mi < 4; ++mi)
; #pragma unroll
;           for (int j = 0; j < 4; ++j) {
;             const int t = mi * 16 + fq * 4 + j;
;             const float rr = sigmoidf_(aR[mi][ni][j] + bba);
;             const float gg = sigmoidf_(aG[mi][ni][j] + bbx);
;             const float xv = bf2f(sX[t * 136 + col]);
;             const float la = -c8 * rr;
;             const float l2 = la + la;
;             const float e1 = la * (1.f + la * (0.5f + la * (0.16666667f + la * (0.041666668f + la * (0.0083333338f + la * 0.0013888889f)))));
;             const float e2 = l2 * (1.f + l2 * (0.5f + l2 * (0.16666667f + l2 * (0.041666668f + l2 * (0.0083333338f + l2 * (0.0013888889f + l2 * 0.0001984127f))))));
;             sR[t * 128 + col] = f2bf(-e1);
;             sG[t * 128 + col] = f2bf(__builtin_amdgcn_sqrtf(fmaxf(-e2, 0.f)) * gg * xv);
;           }
;       }
;     }
;     __syncthreads();
	v_lshlrev_b32_e32 v8, 16, v8
	v_mul_f32_e32 v0, v0, v4
	v_mul_f32_e32 v0, v0, v8
	v_bfe_u32 v4, v0, 16, 1
	v_add3_u32 v0, v0, v4, s71
	ds_write_b16_d16_hi v128, v0 offset:33824
	v_add_f32_e32 v0, v5, v33
	v_mul_f32_e32 v0, 0xbfb8aa3b, v0
	v_exp_f32_e32 v0, v0
	s_nop 0
	v_add_f32_e32 v0, 1.0, v0
	v_div_scale_f32 v4, s[0:1], v0, v0, 1.0
	v_rcp_f32_e32 v5, v4
	s_nop 0
	v_fma_f32 v8, -v4, v5, 1.0
	v_fmac_f32_e32 v5, v8, v5
	v_div_scale_f32 v8, vcc, 1.0, v0, 1.0
	v_mul_f32_e32 v9, v8, v5
	v_fma_f32 v10, -v4, v9, v8
	v_fmac_f32_e32 v9, v10, v5
	v_fma_f32 v4, -v4, v9, v8
	v_div_fmas_f32 v4, v4, v5, v9
	v_div_fixup_f32 v0, v4, v0, 1.0
	v_div_scale_f32 v4, s[0:1], v1, v1, 1.0
	v_rcp_f32_e32 v5, v4
	v_mul_f32_e32 v0, v0, v34
	v_fma_f32 v8, -v4, v5, 1.0
	v_fmac_f32_e32 v5, v8, v5
	v_div_scale_f32 v8, vcc, 1.0, v1, 1.0
	v_mul_f32_e32 v9, v8, v5
	v_fma_f32 v10, -v4, v9, v8
	v_fmac_f32_e32 v9, v10, v5
	v_fma_f32 v4, -v4, v9, v8
	v_fmamk_f32 v8, v0, 0x3ab60b61, v181
	v_div_fmas_f32 v4, v4, v5, v9
	v_add_f32_e32 v5, v0, v0
	v_fmaak_f32 v8, v0, v8, 0x3d2aaaab
	v_fmaak_f32 v8, v0, v8, 0x3e2aaaab
	v_fmamk_f32 v9, v5, 0x39500d01, v191
	v_fma_f32 v8, v0, v8, 0.5
	v_fmaak_f32 v9, v5, v9, 0x3c088889
	v_fma_f32 v8, v0, v8, 1.0
	v_fmaak_f32 v9, v5, v9, 0x3d2aaaab
	v_fmaak_f32 v9, v5, v9, 0x3e2aaaab
	v_mul_f32_e64 v0, v0, -v8
	v_fma_f32 v9, v5, v9, 0.5
	v_bfe_u32 v8, v0, 16, 1
	v_fma_f32 v9, v5, v9, 1.0
	v_add3_u32 v0, v0, v8, s71
	v_div_fixup_f32 v1, v4, v1, 1.0
	ds_read_u16 v4, v137 offset:13088
	ds_write_b16_d16_hi v129, v0 offset:17440
	v_mul_f32_e64 v0, v5, -v9
	v_max_f32_e32 v0, 0, v0
	v_sqrt_f32_e32 v0, v0
	s_waitcnt lgkmcnt(1)
	v_lshlrev_b32_e32 v4, 16, v4
	v_mul_f32_e32 v0, v1, v0
	v_mul_f32_e32 v0, v0, v4
	v_bfe_u32 v1, v0, 16, 1
	v_add3_u32 v0, v0, v1, s71
	ds_write_b16_d16_hi v129, v0 offset:33824
	v_add_f32_e32 v0, v6, v33
	v_mul_f32_e32 v0, 0xbfb8aa3b, v0
	v_exp_f32_e32 v0, v0
	s_nop 0
	v_add_f32_e32 v0, 1.0, v0
	v_div_scale_f32 v1, s[0:1], v0, v0, 1.0
	v_rcp_f32_e32 v4, v1
	s_nop 0
	v_fma_f32 v5, -v1, v4, 1.0
	v_fmac_f32_e32 v4, v5, v4
	v_div_scale_f32 v5, vcc, 1.0, v0, 1.0
	v_mul_f32_e32 v6, v5, v4
	v_fma_f32 v8, -v1, v6, v5
	v_fmac_f32_e32 v6, v8, v4
	v_fma_f32 v1, -v1, v6, v5
	v_div_fmas_f32 v1, v1, v4, v6
	v_div_fixup_f32 v0, v1, v0, 1.0
	v_add_f32_e32 v1, v2, v32
	v_mul_f32_e32 v1, 0xbfb8aa3b, v1
	v_exp_f32_e32 v1, v1
	v_mul_f32_e32 v0, v0, v34
	v_add_f32_e32 v1, 1.0, v1
	v_div_scale_f32 v2, s[0:1], v1, v1, 1.0
	v_rcp_f32_e32 v4, v2
	s_nop 0
	v_fma_f32 v5, -v2, v4, 1.0
	v_fmac_f32_e32 v4, v5, v4
	v_div_scale_f32 v5, vcc, 1.0, v1, 1.0
	v_mul_f32_e32 v6, v5, v4
	v_fma_f32 v8, -v2, v6, v5
	v_fmac_f32_e32 v6, v8, v4
	v_fma_f32 v2, -v2, v6, v5
	v_fmamk_f32 v5, v0, 0x3ab60b61, v181
	v_div_fmas_f32 v2, v2, v4, v6
	v_add_f32_e32 v4, v0, v0
	v_fmaak_f32 v5, v0, v5, 0x3d2aaaab
	v_fmaak_f32 v5, v0, v5, 0x3e2aaaab
	v_fmamk_f32 v6, v4, 0x39500d01, v191
	v_fma_f32 v5, v0, v5, 0.5
	v_fmaak_f32 v6, v4, v6, 0x3c088889
	v_fma_f32 v5, v0, v5, 1.0
	v_fmaak_f32 v6, v4, v6, 0x3d2aaaab
	v_fmaak_f32 v6, v4, v6, 0x3e2aaaab
	v_mul_f32_e64 v0, v0, -v5
	v_fma_f32 v6, v4, v6, 0.5
	v_bfe_u32 v5, v0, 16, 1
	v_fma_f32 v6, v4, v6, 1.0
	v_add3_u32 v0, v0, v5, s71
	v_div_fixup_f32 v1, v2, v1, 1.0
	ds_read_u16 v2, v137 offset:13360
	ds_write_b16_d16_hi v130, v0 offset:17440
	v_mul_f32_e64 v0, v4, -v6
	v_max_f32_e32 v0, 0, v0
	v_sqrt_f32_e32 v0, v0
	s_waitcnt lgkmcnt(1)
	v_lshlrev_b32_e32 v2, 16, v2
	v_mul_f32_e32 v0, v1, v0
	v_mul_f32_e32 v0, v0, v2
	v_bfe_u32 v1, v0, 16, 1
	v_add3_u32 v0, v0, v1, s71
	ds_write_b16_d16_hi v130, v0 offset:33824
	v_add_f32_e32 v0, v7, v33
	v_mul_f32_e32 v0, 0xbfb8aa3b, v0
	v_exp_f32_e32 v0, v0
	s_nop 0
	v_add_f32_e32 v0, 1.0, v0
	v_div_scale_f32 v1, s[0:1], v0, v0, 1.0
	v_rcp_f32_e32 v2, v1
	s_nop 0
	v_fma_f32 v4, -v1, v2, 1.0
	v_fmac_f32_e32 v2, v4, v2
	v_div_scale_f32 v4, vcc, 1.0, v0, 1.0
	v_mul_f32_e32 v5, v4, v2
	v_fma_f32 v6, -v1, v5, v4
	v_fmac_f32_e32 v5, v6, v2
	v_fma_f32 v1, -v1, v5, v4
	v_div_fmas_f32 v1, v1, v2, v5
	v_div_fixup_f32 v0, v1, v0, 1.0
	v_add_f32_e32 v1, v3, v32
	v_mul_f32_e32 v1, 0xbfb8aa3b, v1
	v_exp_f32_e32 v1, v1
	v_mul_f32_e32 v0, v0, v34
	v_add_f32_e32 v1, 1.0, v1
	v_div_scale_f32 v2, s[0:1], v1, v1, 1.0
	v_rcp_f32_e32 v3, v2
	s_mov_b64 s[0:1], -1
	v_fma_f32 v4, -v2, v3, 1.0
	v_fmac_f32_e32 v3, v4, v3
	v_div_scale_f32 v4, vcc, 1.0, v1, 1.0
	v_mul_f32_e32 v5, v4, v3
	v_fma_f32 v6, -v2, v5, v4
	v_fmac_f32_e32 v5, v6, v3
	v_fma_f32 v2, -v2, v5, v4
	v_fmamk_f32 v4, v0, 0x3ab60b61, v181
	v_div_fmas_f32 v2, v2, v3, v5
	v_add_f32_e32 v3, v0, v0
	v_fmaak_f32 v4, v0, v4, 0x3d2aaaab
	v_fmaak_f32 v4, v0, v4, 0x3e2aaaab
	v_fmamk_f32 v5, v3, 0x39500d01, v191
	v_fma_f32 v4, v0, v4, 0.5
	v_fmaak_f32 v5, v3, v5, 0x3c088889
	v_fma_f32 v4, v0, v4, 1.0
	v_fmaak_f32 v5, v3, v5, 0x3d2aaaab
	v_fmaak_f32 v5, v3, v5, 0x3e2aaaab
	v_mul_f32_e64 v0, v0, -v4
	v_fma_f32 v5, v3, v5, 0.5
	v_bfe_u32 v4, v0, 16, 1
	v_fma_f32 v5, v3, v5, 1.0
	v_add3_u32 v0, v0, v4, s71
	v_div_fixup_f32 v1, v2, v1, 1.0
	ds_read_u16 v2, v137 offset:13632
	ds_write_b16_d16_hi v131, v0 offset:17440
	v_mul_f32_e64 v0, v3, -v5
	v_max_f32_e32 v0, 0, v0
	v_sqrt_f32_e32 v0, v0
	s_waitcnt lgkmcnt(1)
	v_lshlrev_b32_e32 v2, 16, v2
	v_mul_f32_e32 v0, v1, v0
	v_mul_f32_e32 v0, v0, v2
	v_bfe_u32 v1, v0, 16, 1
	v_add3_u32 v0, v0, v1, s71
	ds_write_b16_d16_hi v131, v0 offset:33824
	s_waitcnt lgkmcnt(0)
	s_barrier
	s_and_saveexec_b64 s[24:25], s[6:7]
	s_cbranch_execnz .LBB0_372
	s_or_b64 exec, exec, s[24:25]
	s_and_saveexec_b64 s[22:23], s[0:1]
	s_cbranch_execnz .LBB0_396
